# DA attention loops: score max tree rewritten as 32 v_max3/v_max instead of 108 canonicalising v_max
# speedup vs baseline: 1.0102x; 1.0102x over previous
; DI void attn_pass_da(const bfr* __restrict__ P, int b, int tq_wave, int qcol, int kcol, int vcol, int key0, int nkt, char* smem, f32x16 (&o0)[2], f32x16 (&o1)[2]) {
;     ...
;   for (int kt = 0; kt < nkt; ++kt) {
;     bfr* sK = sbase + (kt & 1) * 9216;
;     bfr* sV = sK + 64 * 72;
;     { int c = gt, row = c >> 3, kc = c & 7; *(u32x4*)(sK + row * KP + kc * 8) = kreg[0]; }
;     for (int i = 0; i < 1; ++i) {
;       int c = gt, row = c >> 3, kc = c & 7;
;       unsigned wds[4] = {vreg[i].x, vreg[i].y, vreg[i].z, vreg[i].w};
; #pragma unroll
;       for (int e = 0; e < 4; ++e) {
;         sV[(kc * 8 + 2 * e) * 72 + (row ^ (kc << 3))] = (bfr)(wds[e] & 0xffffu);
;         sV[(kc * 8 + 2 * e + 1) * 72 + (row ^ (kc << 3))] = (bfr)(wds[e] >> 16);
;       }
;     }
;     __syncthreads();
;     if (kt + 1 < nkt) {
;       const bfr* Pn = Pb + (size_t)(kt + 1) * 64 * PW;
;       { int c = gt, row = c >> 3, kc = c & 7; kreg[0] = *(const u32x4*)(Pn + (size_t)row * PW + kcol + kc * 8); vreg[0] = *(const u32x4*)(Pn + (size_t)row * PW + vcol + kc * 8); }
;     }
;     f32x16 s0[2], s1[2];
; #pragma unroll
;     for (int t2 = 0; t2 < 2; ++t2) {
; #pragma unroll
;       for (int i = 0; i < 16; ++i) { s0[t2][i] = 0.f; s1[t2][i] = 0.f; }
; #pragma unroll
;       for (int ks = 0; ks < 2; ++ks) {
;         bf16x8 a0 = *(const bf16x8*)(sK + (t2 * 32 + r) * KP + ks * 16 + h * 8);
;         bf16x8 a1 = *(const bf16x8*)(sK + (t2 * 32 + r) * KP + 32 + ks * 16 + h * 8);
;         s0[t2] = MFMA32(a0, qf[ks], s0[t2]);
;         s1[t2] = MFMA32(a1, qf[2 + ks], s1[t2]);
;       }
;     }
;     float mx0 = s0[0][0], mx1 = s1[0][0];
; #pragma unroll
;     for (int i = 0; i < 16; ++i) { mx0 = fmaxf(mx0, fmaxf(s0[0][i], s0[1][i])); mx1 = fmaxf(mx1, fmaxf(s1[0][i], s1[1][i])); }
;     mx0 = fmaxf(mx0, __shfl_xor(mx0, 32)); mx1 = fmaxf(mx1, __shfl_xor(mx1, 32));
;     const float mn0 = fmaxf(m0, mx0), mn1 = fmaxf(m1, mx1);
;     const float al0 = __builtin_amdgcn_exp2f(m0 - mn0), al1 = __builtin_amdgcn_exp2f(m1 - mn1);
;     m0 = mn0; m1 = mn1;
;     float ps0 = 0.f, ps1 = 0.f;
; #pragma unroll
;     for (int i = 0; i < 16; ++i) {
;       s0[0][i] = __builtin_amdgcn_exp2f(s0[0][i] - mn0); ps0 += s0[0][i];
;       s0[1][i] = __builtin_amdgcn_exp2f(s0[1][i] - mn0); ps0 += s0[1][i];
;       s1[0][i] = __builtin_amdgcn_exp2f(s1[0][i] - mn1); ps1 += s1[0][i];
.LBB0_408:
	s_bitcmp1_b32 s14, 0
	s_cselect_b32 s15, 0x4800, 0
	s_add_i32 s15, s15, 0
	v_add3_u32 v64, s15, v206, v152
	v_add_u32_e32 v194, s15, v205
	s_waitcnt vmcnt(1)
	ds_write_b128 v64, v[148:151]
	v_add3_u32 v64, s15, v207, v208
	v_add3_u32 v65, s15, v208, v207
	v_add_u32_e32 v100, v194, v204
	s_waitcnt vmcnt(0)
	ds_write_b16 v64, v144 offset:9216
	ds_write_b16_d16_hi v65, v144 offset:9360
	ds_write_b16 v64, v145 offset:9504
	ds_write_b16_d16_hi v65, v145 offset:9648
	ds_write_b16 v64, v146 offset:9792
	ds_write_b16_d16_hi v65, v146 offset:9936
	ds_write_b16 v64, v147 offset:10080
	ds_write_b16_d16_hi v65, v147 offset:10224
	s_waitcnt lgkmcnt(0)
	s_barrier
	global_load_dwordx4 v[148:151], v[158:159], off
	global_load_dwordx4 v[144:147], v[158:159], off offset:512
	ds_read_b128 v[64:67], v100 offset:64
	ds_read_b128 v[68:71], v100
	ds_read_b128 v[96:99], v100 offset:32
	ds_read_b128 v[100:103], v100 offset:96
	s_waitcnt lgkmcnt(2)
	v_mfma_f32_32x32x16_bf16 v[80:95], v[68:71], v[140:143], 0
	v_add_u32_e32 v195, s15, v211
	v_add_u32_e32 v192, v195, v204
	v_mov_b32_e32 v160, v209
	v_mov_b32_e32 v161, v210
	s_add_i32 s14, s14, 1
	v_lshl_add_u64 v[158:159], v[158:159], 0, s[16:17]
	s_cmp_lg_u32 s14, 3
	v_mfma_f32_32x32x16_bf16 v[64:79], v[64:67], v[136:139], 0
	s_waitcnt lgkmcnt(1)
	v_mfma_f32_32x32x16_bf16 v[80:95], v[96:99], v[132:135], v[80:95]
	s_waitcnt lgkmcnt(0)
	v_mfma_f32_32x32x16_bf16 v[64:79], v[100:103], v[128:131], v[64:79]
	ds_read_b128 v[96:99], v192 offset:64
	ds_read_b128 v[100:103], v192
	ds_read_b128 v[212:215], v192 offset:32
	ds_read_b128 v[216:219], v192 offset:96
	s_nop 5
	v_max3_f32 v209, v80, v81, v82
	v_max3_f32 v209, v209, v83, v84
	v_max3_f32 v193, v64, v65, v66
	s_waitcnt lgkmcnt(2)
	v_mfma_f32_32x32x16_bf16 v[112:127], v[100:103], v[140:143], 0
	v_mfma_f32_32x32x16_bf16 v[96:111], v[96:99], v[136:139], 0
	s_waitcnt lgkmcnt(1)
	v_mfma_f32_32x32x16_bf16 v[112:127], v[212:215], v[132:135], v[112:127]
	v_max3_f32 v193, v193, v67, v68
	v_max3_f32 v209, v209, v85, v86
	s_waitcnt lgkmcnt(0)
	v_mfma_f32_32x32x16_bf16 v[96:111], v[216:219], v[128:131], v[96:111]
	v_max3_f32 v193, v193, v69, v70
	v_max3_f32 v209, v209, v87, v88
	v_max3_f32 v193, v193, v71, v72
	v_max3_f32 v209, v209, v89, v90
	v_max3_f32 v193, v193, v73, v74
	v_max3_f32 v209, v209, v91, v92
	v_max3_f32 v193, v193, v75, v76
	v_max3_f32 v209, v209, v93, v94
	v_max3_f32 v193, v193, v77, v78
	v_max3_f32 v209, v209, v95, v112
	v_max3_f32 v209, v209, v113, v114
	v_max3_f32 v209, v209, v115, v116
	v_max3_f32 v209, v209, v117, v118
	v_max3_f32 v209, v209, v119, v120
	v_max3_f32 v209, v209, v121, v122
	v_max3_f32 v209, v209, v123, v124
	v_max3_f32 v209, v209, v125, v126
	v_max_f32_e32 v192, v209, v127
	v_max3_f32 v193, v193, v79, v96
	v_max3_f32 v193, v193, v97, v98
	v_max3_f32 v193, v193, v99, v100
	v_max3_f32 v193, v193, v101, v102
	v_max3_f32 v193, v193, v103, v104
	v_max3_f32 v193, v193, v105, v106
	v_max3_f32 v193, v193, v107, v108
	v_max3_f32 v193, v193, v109, v110
	v_max_f32_e32 v193, v193, v111
	ds_bpermute_b32 v210, v166, v193
	ds_bpermute_b32 v209, v166, v192
	s_waitcnt lgkmcnt(1)
	v_max3_f32 v210, v161, v193, v210
	s_waitcnt lgkmcnt(0)
	v_max3_f32 v209, v160, v192, v209
	v_sub_f32_e32 v64, v64, v210
	v_sub_f32_e32 v80, v80, v209
	v_exp_f32_e32 v193, v64
	v_sub_f32_e32 v64, v96, v210
	v_exp_f32_e32 v192, v80
	v_sub_f32_e32 v80, v112, v209
	v_exp_f32_e32 v213, v64
	v_sub_f32_e32 v64, v81, v209
	v_exp_f32_e32 v212, v80
	v_exp_f32_e32 v80, v64
	v_sub_f32_e32 v64, v113, v209
	v_exp_f32_e32 v96, v64
	v_sub_f32_e32 v64, v65, v210
	v_exp_f32_e32 v81, v64
	v_sub_f32_e32 v64, v97, v210
	v_exp_f32_e32 v97, v64
	v_sub_f32_e32 v64, v82, v209
	v_exp_f32_e32 v112, v64
	v_sub_f32_e32 v64, v114, v209
	v_exp_f32_e32 v214, v64
	v_sub_f32_e32 v64, v66, v210
	v_exp_f32_e32 v113, v64
	v_sub_f32_e32 v64, v98, v210
	v_exp_f32_e32 v215, v64
	v_sub_f32_e32 v64, v83, v209
	v_exp_f32_e32 v82, v64
	v_sub_f32_e32 v64, v115, v209
	v_exp_f32_e32 v98, v64
	v_sub_f32_e32 v64, v67, v210
	v_exp_f32_e32 v83, v64
	v_sub_f32_e32 v64, v99, v210
	v_exp_f32_e32 v99, v64
	v_sub_f32_e32 v64, v84, v209
	v_exp_f32_e32 v114, v64
	v_sub_f32_e32 v64, v116, v209
	v_exp_f32_e32 v216, v64
	v_sub_f32_e32 v64, v68, v210
	v_exp_f32_e32 v115, v64
	v_sub_f32_e32 v64, v100, v210
	v_exp_f32_e32 v217, v64
	v_sub_f32_e32 v64, v85, v209
	v_exp_f32_e32 v84, v64
	v_sub_f32_e32 v64, v117, v209
	v_exp_f32_e32 v100, v64
	v_sub_f32_e32 v64, v69, v210
	v_exp_f32_e32 v85, v64
	v_sub_f32_e32 v64, v101, v210
	v_exp_f32_e32 v101, v64
	v_sub_f32_e32 v64, v86, v209
	v_exp_f32_e32 v116, v64
	v_sub_f32_e32 v64, v118, v209
	v_exp_f32_e32 v218, v64
	v_sub_f32_e32 v64, v70, v210
	v_exp_f32_e32 v117, v64
	v_sub_f32_e32 v64, v102, v210
	v_exp_f32_e32 v219, v64
	v_sub_f32_e32 v64, v87, v209
	v_exp_f32_e32 v70, v64
	v_sub_f32_e32 v64, v119, v209
	v_exp_f32_e32 v86, v64
	v_sub_f32_e32 v64, v71, v210
	v_exp_f32_e32 v71, v64
	v_sub_f32_e32 v64, v103, v210
	v_exp_f32_e32 v87, v64
	v_sub_f32_e32 v64, v88, v209
	v_exp_f32_e32 v102, v64
	v_sub_f32_e32 v64, v120, v209
	v_exp_f32_e32 v118, v64
	v_sub_f32_e32 v64, v72, v210
	v_exp_f32_e32 v103, v64
	v_sub_f32_e32 v64, v104, v210
	v_exp_f32_e32 v119, v64
	v_sub_f32_e32 v64, v89, v209
	v_exp_f32_e32 v88, v64
	v_sub_f32_e32 v64, v121, v209
	v_exp_f32_e32 v104, v64
	v_sub_f32_e32 v64, v73, v210
	v_exp_f32_e32 v89, v64
	v_sub_f32_e32 v64, v105, v210
	v_exp_f32_e32 v105, v64
	v_sub_f32_e32 v64, v90, v209
	v_exp_f32_e32 v120, v64
	v_sub_f32_e32 v64, v122, v209
	v_exp_f32_e32 v220, v64
	v_sub_f32_e32 v64, v74, v210
	v_exp_f32_e32 v121, v64
	v_sub_f32_e32 v64, v106, v210
	v_exp_f32_e32 v221, v64
; #define MFMA32(a, b, c) __builtin_amdgcn_mfma_f32_32x32x16_bf16((a), (b), (c), 0, 0, 0)
; DI void attn_pass_da(const bfr* __restrict__ P, int b, int tq_wave, int qcol, int kcol, int vcol, int key0, int nkt, char* smem, f32x16 (&o0)[2], f32x16 (&o1)[2]) {
;     ...
;     const float mn0 = fmaxf(m0, mx0), mn1 = fmaxf(m1, mx1);
;     const float al0 = __builtin_amdgcn_exp2f(m0 - mn0), al1 = __builtin_amdgcn_exp2f(m1 - mn1);
;     m0 = mn0; m1 = mn1;
;     float ps0 = 0.f, ps1 = 0.f;
; #pragma unroll
;     for (int i = 0; i < 16; ++i) {
;       s0[0][i] = __builtin_amdgcn_exp2f(s0[0][i] - mn0); ps0 += s0[0][i];
;       s0[1][i] = __builtin_amdgcn_exp2f(s0[1][i] - mn0); ps0 += s0[1][i];
;       s1[0][i] = __builtin_amdgcn_exp2f(s1[0][i] - mn1); ps1 += s1[0][i];
;       s1[1][i] = __builtin_amdgcn_exp2f(s1[1][i] - mn1); ps1 += s1[1][i];
;     }
;     l0 = l0 * al0 + ps0; l1 = l1 * al1 + ps1;
; #pragma unroll
;     for (int i = 0; i < 16; ++i) { acc0[0][i] *= al0; acc0[1][i] *= al0; acc1[0][i] *= al1; acc1[1][i] *= al1; }
; #pragma unroll
;     for (int t2 = 0; t2 < 2; ++t2)
; #pragma unroll
;       for (int j = 0; j < 2; ++j) {
;         u32x4 pk0, pk1;
;         pk0.x = pack2(s0[t2][8 * j + 0], s0[t2][8 * j + 1]); pk0.y = pack2(s0[t2][8 * j + 2], s0[t2][8 * j + 3]);
;         pk0.z = pack2(s0[t2][8 * j + 4], s0[t2][8 * j + 5]); pk0.w = pack2(s0[t2][8 * j + 6], s0[t2][8 * j + 7]);
;         pk1.x = pack2(s1[t2][8 * j + 0], s1[t2][8 * j + 1]); pk1.y = pack2(s1[t2][8 * j + 2], s1[t2][8 * j + 3]);
;         pk1.z = pack2(s1[t2][8 * j + 4], s1[t2][8 * j + 5]); pk1.w = pack2(s1[t2][8 * j + 6], s1[t2][8 * j + 7]);
;         const bf16x8 pf0 = __builtin_bit_cast(bf16x8, pk0), pf1 = __builtin_bit_cast(bf16x8, pk1);
; #pragma unroll
;         for (int dt = 0; dt < 2; ++dt) {
;           const int vsw = (((dt * 32 + r) >> 3) & 7) << 3;
;           const bfr* vrow = sV + (dt * 32 + r) * 72;
;           s16x4 lo = *(const s16x4*)(vrow + ((t2 * 32 + 16 * j + 4 * h) ^ vsw));
;           s16x4 hi = *(const s16x4*)(vrow + ((t2 * 32 + 16 * j + 4 * h + 8) ^ vsw));
;           bf16x8 vf = __builtin_shufflevector(lo, hi, 0, 1, 2, 3, 4, 5, 6, 7);
;           acc0[dt] = MFMA32(vf, pf0, acc0[dt]);
;           acc1[dt] = MFMA32(vf, pf1, acc1[dt]);
;         }
;       }
	v_sub_f32_e32 v64, v91, v209
	v_exp_f32_e32 v90, v64
	v_sub_f32_e32 v64, v123, v209
	v_exp_f32_e32 v106, v64
	v_sub_f32_e32 v64, v75, v210
	v_exp_f32_e32 v91, v64
	v_sub_f32_e32 v64, v107, v210
	v_exp_f32_e32 v107, v64
	v_sub_f32_e32 v64, v92, v209
	v_exp_f32_e32 v122, v64
	v_sub_f32_e32 v64, v124, v209
	v_exp_f32_e32 v222, v64
	v_sub_f32_e32 v64, v76, v210
	v_exp_f32_e32 v123, v64
	v_sub_f32_e32 v64, v108, v210
	v_exp_f32_e32 v223, v64
	v_sub_f32_e32 v64, v93, v209
	v_exp_f32_e32 v92, v64
	v_sub_f32_e32 v64, v125, v209
	v_exp_f32_e32 v108, v64
	v_sub_f32_e32 v64, v77, v210
	v_exp_f32_e32 v93, v64
	v_sub_f32_e32 v64, v109, v210
	v_exp_f32_e32 v109, v64
	v_sub_f32_e32 v64, v94, v209
	v_exp_f32_e32 v124, v64
	v_sub_f32_e32 v64, v126, v209
	v_exp_f32_e32 v224, v64
	v_sub_f32_e32 v64, v78, v210
	v_exp_f32_e32 v125, v64
	v_sub_f32_e32 v64, v110, v210
	v_exp_f32_e32 v225, v64
	v_sub_f32_e32 v64, v95, v209
	v_exp_f32_e32 v94, v64
	v_sub_f32_e32 v64, v127, v209
	v_exp_f32_e32 v110, v64
	v_sub_f32_e32 v64, v79, v210
	v_exp_f32_e32 v95, v64
	v_sub_f32_e32 v64, v111, v210
	v_exp_f32_e32 v111, v64
	v_pk_add_f32 v[64:65], v[192:193], 0 op_sel_hi:[1,0]
	v_sub_f32_e32 v161, v161, v210
	v_pk_add_f32 v[64:65], v[212:213], v[64:65]
	v_exp_f32_e32 v161, v161
	v_pk_add_f32 v[64:65], v[80:81], v[64:65]
	v_lshl_add_u32 v74, v180, 1, v194
	v_pk_add_f32 v[64:65], v[96:97], v[64:65]
	v_lshl_add_u32 v76, v179, 1, v195
	v_pk_add_f32 v[64:65], v[112:113], v[64:65]
	v_lshl_add_u32 v78, v178, 1, v195
	v_pk_add_f32 v[64:65], v[214:215], v[64:65]
	v_sub_f32_e32 v160, v160, v209
	v_pk_add_f32 v[64:65], v[82:83], v[64:65]
	v_exp_f32_e32 v160, v160
	v_pk_add_f32 v[64:65], v[98:99], v[64:65]
	v_pk_mul_f32 v[62:63], v[62:63], v[160:161] op_sel_hi:[1,0]
	v_pk_add_f32 v[64:65], v[114:115], v[64:65]
	v_pk_mul_f32 v[60:61], v[60:61], v[160:161] op_sel_hi:[1,0]
	v_pk_add_f32 v[64:65], v[216:217], v[64:65]
	v_pk_mul_f32 v[58:59], v[58:59], v[160:161] op_sel_hi:[1,0]
	v_pk_add_f32 v[64:65], v[84:85], v[64:65]
	v_pk_mul_f32 v[56:57], v[56:57], v[160:161] op_sel_hi:[1,0]
	v_pk_add_f32 v[64:65], v[100:101], v[64:65]
	v_pk_mul_f32 v[54:55], v[54:55], v[160:161] op_sel_hi:[1,0]
	v_pk_add_f32 v[64:65], v[116:117], v[64:65]
	v_pk_mul_f32 v[52:53], v[52:53], v[160:161] op_sel_hi:[1,0]
	v_pk_add_f32 v[64:65], v[218:219], v[64:65]
	v_pk_mul_f32 v[50:51], v[50:51], v[160:161] op_sel_hi:[1,0]
	v_pk_add_f32 v[64:65], v[70:71], v[64:65]
	v_pk_mul_f32 v[48:49], v[48:49], v[160:161] op_sel_hi:[1,0]
	v_pk_add_f32 v[64:65], v[86:87], v[64:65]
	v_pk_mul_f32 v[30:31], v[30:31], v[160:161] op_sel_hi:[1,0]
	v_pk_add_f32 v[64:65], v[102:103], v[64:65]
	v_pk_mul_f32 v[28:29], v[28:29], v[160:161] op_sel_hi:[1,0]
	v_pk_add_f32 v[64:65], v[118:119], v[64:65]
	v_pk_mul_f32 v[26:27], v[26:27], v[160:161] op_sel_hi:[1,0]
	v_pk_add_f32 v[64:65], v[88:89], v[64:65]
	v_pk_mul_f32 v[24:25], v[24:25], v[160:161] op_sel_hi:[1,0]
	v_pk_add_f32 v[64:65], v[104:105], v[64:65]
	v_pk_mul_f32 v[22:23], v[22:23], v[160:161] op_sel_hi:[1,0]
	v_pk_add_f32 v[64:65], v[120:121], v[64:65]
	v_pk_mul_f32 v[20:21], v[20:21], v[160:161] op_sel_hi:[1,0]
	v_pk_add_f32 v[126:127], v[220:221], v[64:65]
	v_cvt_pk_bf16_f32 v64, v192, v80
	v_cvt_pk_bf16_f32 v65, v112, v82
	v_lshl_add_u32 v112, v181, 1, v194
	v_cvt_pk_bf16_f32 v66, v114, v84
	v_cvt_pk_bf16_f32 v67, v116, v70
	v_cvt_pk_bf16_f32 v68, v193, v81
	v_cvt_pk_bf16_f32 v69, v113, v83
	v_cvt_pk_bf16_f32 v70, v115, v85
	v_cvt_pk_bf16_f32 v71, v117, v71
	ds_read_b64 v[72:73], v112 offset:9216
	ds_read_b64 v[74:75], v74 offset:9216
	ds_read_b64 v[76:77], v76 offset:9216
	ds_read_b64 v[78:79], v78 offset:9216
	v_mov_b32_e32 v82, v161
	v_pk_mul_f32 v[46:47], v[46:47], v[82:83] op_sel_hi:[1,0]
	v_pk_mul_f32 v[44:45], v[44:45], v[82:83] op_sel_hi:[1,0]
	v_pk_mul_f32 v[42:43], v[42:43], v[82:83] op_sel_hi:[1,0]
	v_pk_mul_f32 v[40:41], v[40:41], v[82:83] op_sel_hi:[1,0]
	v_pk_mul_f32 v[38:39], v[38:39], v[82:83] op_sel_hi:[1,0]
	v_pk_mul_f32 v[36:37], v[36:37], v[82:83] op_sel_hi:[1,0]
	v_pk_mul_f32 v[34:35], v[34:35], v[82:83] op_sel_hi:[1,0]
	v_pk_mul_f32 v[32:33], v[32:33], v[82:83] op_sel_hi:[1,0]
	v_pk_mul_f32 v[14:15], v[14:15], v[82:83] op_sel_hi:[1,0]
	v_pk_mul_f32 v[12:13], v[12:13], v[82:83] op_sel_hi:[1,0]
	v_pk_mul_f32 v[10:11], v[10:11], v[82:83] op_sel_hi:[1,0]
	v_pk_mul_f32 v[8:9], v[8:9], v[82:83] op_sel_hi:[1,0]
	v_pk_mul_f32 v[6:7], v[6:7], v[82:83] op_sel_hi:[1,0]
	v_pk_mul_f32 v[4:5], v[4:5], v[82:83] op_sel_hi:[1,0]
	v_pk_mul_f32 v[2:3], v[2:3], v[82:83] op_sel_hi:[1,0]
	v_pk_mul_f32 v[0:1], v[0:1], v[82:83] op_sel_hi:[1,0]
	v_pk_add_f32 v[82:83], v[90:91], v[126:127]
	s_waitcnt lgkmcnt(2)
	v_mfma_f32_32x32x16_bf16 v[48:63], v[72:75], v[64:67], v[48:63]
	v_add_f32_e64 v82, v106, v82
	v_add_f32_e64 v83, v107, v83
	v_cvt_pk_bf16_f32 v80, v102, v88
	v_lshl_add_u32 v88, v177, 1, v194
	v_add_f32_e64 v82, v122, v82
	v_add_f32_e64 v83, v123, v83
	v_pk_mul_f32 v[18:19], v[18:19], v[160:161] op_sel_hi:[1,0]
	v_pk_add_f32 v[82:83], v[222:223], v[82:83]
	v_pk_mul_f32 v[16:17], v[16:17], v[160:161] op_sel_hi:[1,0]
	v_pk_add_f32 v[82:83], v[92:93], v[82:83]
	v_mfma_f32_32x32x16_bf16 v[32:47], v[72:75], v[68:71], v[32:47]
	v_add_f32_e64 v82, v108, v82
	v_add_f32_e64 v83, v109, v83
	v_cvt_pk_bf16_f32 v81, v120, v90
	v_lshl_add_u32 v102, v176, 1, v194
	v_add_f32_e64 v82, v124, v82
	v_add_f32_e64 v83, v125, v83
	v_lshl_add_u32 v113, v175, 1, v195
	v_pk_add_f32 v[82:83], v[224:225], v[82:83]
	v_lshl_add_u32 v114, v174, 1, v195
	v_pk_add_f32 v[82:83], v[94:95], v[82:83]
	s_waitcnt lgkmcnt(0)
; DI void attn_pass_da(const bfr* __restrict__ P, int b, int tq_wave, int qcol, int kcol, int vcol, int key0, int nkt, char* smem, f32x16 (&o0)[2], f32x16 (&o1)[2]) {
;     ...
;   for (int kt = 0; kt < nkt; ++kt) {
;     bfr* sK = sbase + (kt & 1) * 9216;
;     bfr* sV = sK + 64 * 72;
;     { int c = gt, row = c >> 3, kc = c & 7; *(u32x4*)(sK + row * KP + kc * 8) = kreg[0]; }
;     for (int i = 0; i < 1; ++i) {
;       int c = gt, row = c >> 3, kc = c & 7;
;       unsigned wds[4] = {vreg[i].x, vreg[i].y, vreg[i].z, vreg[i].w};
; #pragma unroll
;       for (int e = 0; e < 4; ++e) {
;         sV[(kc * 8 + 2 * e) * 72 + (row ^ (kc << 3))] = (bfr)(wds[e] & 0xffffu);
;         sV[(kc * 8 + 2 * e + 1) * 72 + (row ^ (kc << 3))] = (bfr)(wds[e] >> 16);
;       }
;     }
;     __syncthreads();
;     if (kt + 1 < nkt) {
;       const bfr* Pn = Pb + (size_t)(kt + 1) * 64 * PW;
;       { int c = gt, row = c >> 3, kc = c & 7; kreg[0] = *(const u32x4*)(Pn + (size_t)row * PW + kcol + kc * 8); vreg[0] = *(const u32x4*)(Pn + (size_t)row * PW + vcol + kc * 8); }
;     }
;     f32x16 s0[2], s1[2];
; #pragma unroll
;     for (int t2 = 0; t2 < 2; ++t2) {
; #pragma unroll
;     ...
;     for (int t2 = 0; t2 < 2; ++t2)
; #pragma unroll
;       for (int j = 0; j < 2; ++j) {
;         u32x4 pk0, pk1;
;         pk0.x = pack2(s0[t2][8 * j + 0], s0[t2][8 * j + 1]); pk0.y = pack2(s0[t2][8 * j + 2], s0[t2][8 * j + 3]);
;         pk0.z = pack2(s0[t2][8 * j + 4], s0[t2][8 * j + 5]); pk0.w = pack2(s0[t2][8 * j + 6], s0[t2][8 * j + 7]);
;         pk1.x = pack2(s1[t2][8 * j + 0], s1[t2][8 * j + 1]); pk1.y = pack2(s1[t2][8 * j + 2], s1[t2][8 * j + 3]);
;         pk1.z = pack2(s1[t2][8 * j + 4], s1[t2][8 * j + 5]); pk1.w = pack2(s1[t2][8 * j + 6], s1[t2][8 * j + 7]);
;         const bf16x8 pf0 = __builtin_bit_cast(bf16x8, pk0), pf1 = __builtin_bit_cast(bf16x8, pk1);
; #pragma unroll
;         for (int dt = 0; dt < 2; ++dt) {
;           const int vsw = (((dt * 32 + r) >> 3) & 7) << 3;
;           const bfr* vrow = sV + (dt * 32 + r) * 72;
;           s16x4 lo = *(const s16x4*)(vrow + ((t2 * 32 + 16 * j + 4 * h) ^ vsw));
;           s16x4 hi = *(const s16x4*)(vrow + ((t2 * 32 + 16 * j + 4 * h + 8) ^ vsw));
;           bf16x8 vf = __builtin_shufflevector(lo, hi, 0, 1, 2, 3, 4, 5, 6, 7);
;           acc0[dt] = MFMA32(vf, pf0, acc0[dt]);
;           acc1[dt] = MFMA32(vf, pf1, acc1[dt]);
;         }
;       }
	v_mfma_f32_32x32x16_bf16 v[16:31], v[76:79], v[64:67], v[16:31]
	v_add_f32_e64 v84, v110, v82
	v_add_f32_e64 v85, v111, v83
	v_cvt_pk_bf16_f32 v82, v122, v92
	v_cvt_pk_bf16_f32 v83, v124, v94
	v_cvt_pk_bf16_f32 v64, v103, v89
	v_cvt_pk_bf16_f32 v65, v121, v91
	v_cvt_pk_bf16_f32 v66, v123, v93
	v_cvt_pk_bf16_f32 v67, v125, v95
	v_mfma_f32_32x32x16_bf16 v[0:15], v[76:79], v[68:71], v[0:15]
	ds_read_b64 v[68:69], v88 offset:9216
	ds_read_b64 v[70:71], v102 offset:9216
	v_lshl_add_u32 v115, v173, 1, v194
	v_lshl_add_u32 v116, v172, 1, v195
	v_lshl_add_u32 v117, v171, 1, v195
	v_lshl_add_u32 v120, v169, 1, v194
	v_lshl_add_u32 v192, v170, 1, v194
	v_lshl_add_u32 v193, v168, 1, v195
	s_waitcnt lgkmcnt(0)
	v_mfma_f32_32x32x16_bf16 v[48:63], v[68:71], v[80:83], v[48:63]
	v_lshl_add_u32 v194, v167, 1, v195
	v_fma_f32 v156, v156, v160, v84
	v_fma_f32 v157, v157, v161, v85
	v_mfma_f32_32x32x16_bf16 v[32:47], v[68:71], v[64:67], v[32:47]
	ds_read_b64 v[68:69], v113 offset:9216
	ds_read_b64 v[70:71], v114 offset:9216
	s_waitcnt lgkmcnt(0)
	v_mfma_f32_32x32x16_bf16 v[16:31], v[68:71], v[80:83], v[16:31]
	v_mfma_f32_32x32x16_bf16 v[0:15], v[68:71], v[64:67], v[0:15]
	v_cvt_pk_bf16_f32 v64, v212, v96
	v_cvt_pk_bf16_f32 v65, v214, v98
	v_cvt_pk_bf16_f32 v66, v216, v100
	v_cvt_pk_bf16_f32 v67, v218, v86
	v_cvt_pk_bf16_f32 v68, v213, v97
	v_cvt_pk_bf16_f32 v69, v215, v99
	v_cvt_pk_bf16_f32 v70, v217, v101
	v_cvt_pk_bf16_f32 v71, v219, v87
	ds_read_b64 v[72:73], v112 offset:9280
	ds_read_b64 v[74:75], v115 offset:9216
	s_waitcnt lgkmcnt(0)
	v_mfma_f32_32x32x16_bf16 v[48:63], v[72:75], v[64:67], v[48:63]
	v_mfma_f32_32x32x16_bf16 v[32:47], v[72:75], v[68:71], v[32:47]
	ds_read_b64 v[72:73], v116 offset:9216
	ds_read_b64 v[74:75], v117 offset:9216
	s_waitcnt lgkmcnt(0)
	v_mfma_f32_32x32x16_bf16 v[16:31], v[72:75], v[64:67], v[16:31]
	v_cvt_pk_bf16_f32 v64, v118, v104
	v_cvt_pk_bf16_f32 v65, v220, v106
	v_cvt_pk_bf16_f32 v66, v222, v108
	v_cvt_pk_bf16_f32 v67, v224, v110
	v_mfma_f32_32x32x16_bf16 v[0:15], v[72:75], v[68:71], v[0:15]
	v_cvt_pk_bf16_f32 v68, v119, v105
	v_cvt_pk_bf16_f32 v69, v221, v107
	v_cvt_pk_bf16_f32 v70, v223, v109
	v_cvt_pk_bf16_f32 v71, v225, v111
	ds_read_b64 v[72:73], v120 offset:9216
	ds_read_b64 v[74:75], v192 offset:9216
	s_waitcnt lgkmcnt(0)
	v_mfma_f32_32x32x16_bf16 v[48:63], v[72:75], v[64:67], v[48:63]
	v_mfma_f32_32x32x16_bf16 v[32:47], v[72:75], v[68:71], v[32:47]
	ds_read_b64 v[72:73], v193 offset:9216
	ds_read_b64 v[74:75], v194 offset:9216
	s_waitcnt lgkmcnt(0)
	v_mfma_f32_32x32x16_bf16 v[16:31], v[72:75], v[64:67], v[16:31]
	v_mfma_f32_32x32x16_bf16 v[0:15], v[72:75], v[68:71], v[0:15]
	s_cbranch_scc1 .LBB0_408
	v_add3_u32 v64, 0, v206, v152
	s_waitcnt vmcnt(1)
	ds_write_b128 v64, v[148:151] offset:18432
	v_add3_u32 v64, 0, v207, v208
	v_add3_u32 v65, 0, v208, v207
	s_waitcnt vmcnt(0)
	ds_write_b16 v64, v144 offset:27648
	ds_write_b16_d16_hi v65, v144 offset:27792
	ds_write_b16 v64, v145 offset:27936
	ds_write_b16_d16_hi v65, v145 offset:28080
	ds_write_b16 v64, v146 offset:28224
	ds_write_b16_d16_hi v65, v146 offset:28368
	ds_write_b16 v64, v147 offset:28512
	ds_write_b16_d16_hi v65, v147 offset:28656
	v_add_u32_e32 v144, 0, v205
	v_add_u32_e32 v102, v144, v204
	s_waitcnt lgkmcnt(0)
	s_barrier
	ds_read_b128 v[64:67], v102 offset:18432
	ds_read_b128 v[96:99], v102 offset:18464
	s_waitcnt lgkmcnt(1)
	v_mfma_f32_32x32x16_bf16 v[64:79], v[64:67], v[140:143], 0
	ds_read_b128 v[80:83], v102 offset:18496
	v_readlane_b32 s14, v203, 16
	v_readlane_b32 s15, v203, 48
	v_add_u32_e32 v145, 0x1200, v144
	v_mov_b32_e32 v100, s14
	v_mov_b32_e32 v101, s15
	v_pk_add_f32 v[100:101], s[12:13], v[100:101]
	s_mov_b32 s14, 0x3fb8aa3b
	v_add_f32_e32 v146, v100, v101
	v_mul_f32_e32 v104, 0x3fb8aa3b, v146
	v_fma_f32 v105, v146, s14, -v104
	v_rndne_f32_e32 v106, v104
	s_waitcnt lgkmcnt(1)
	v_mfma_f32_32x32x16_bf16 v[64:79], v[96:99], v[132:135], v[64:79]
	v_fmac_f32_e32 v105, 0x32a5705f, v146
	v_sub_f32_e32 v96, v104, v106
	v_add_u32_e32 v147, v145, v204
	v_add_f32_e32 v104, v96, v105
	ds_read_b128 v[96:99], v147 offset:18432
	ds_read_b128 v[100:103], v102 offset:18528
	ds_read_b128 v[112:115], v147 offset:18496
	s_waitcnt lgkmcnt(3)
	v_mfma_f32_32x32x16_bf16 v[80:95], v[80:83], v[136:139], 0
	v_readlane_b32 s12, v202, 16
	v_readlane_b32 s13, v202, 48
	s_mov_b32 s15, 0xc2ce8ed0
	v_mov_b32_e32 v116, s12
	v_mov_b32_e32 v117, s13
	v_pk_add_f32 v[116:117], s[10:11], v[116:117]
	v_cmp_ngt_f32_e32 vcc, s15, v146
	s_waitcnt lgkmcnt(1)
	v_mfma_f32_32x32x16_bf16 v[80:95], v[100:103], v[128:131], v[80:95]
	v_exp_f32_e32 v100, v104
	v_cvt_i32_f32_e32 v101, v106
	v_add_f32_e32 v149, v116, v117
	v_mul_f32_e32 v150, 0x3fb8aa3b, v149
	v_rndne_f32_e32 v151, v150
	v_ldexp_f32 v148, v100, v101
	s_mov_b32 s10, 0x42b17218
	s_waitcnt lgkmcnt(0)
	v_mfma_f32_32x32x16_bf16 v[112:127], v[112:115], v[136:139], 0
	v_fma_f32 v136, v149, s14, -v150
	v_fmac_f32_e32 v136, 0x32a5705f, v149
	v_sub_f32_e32 v137, v150, v151
	v_add_f32_e32 v136, v137, v136
	v_exp_f32_e32 v150, v136
	ds_read_b128 v[136:139], v147 offset:18528
	v_readlane_b32 s12, v253, 28
	v_mfma_f32_32x32x16_bf16 v[96:111], v[96:99], v[140:143], 0
	ds_read_b128 v[140:143], v147 offset:18464
	v_readlane_b32 s13, v253, 29
	s_waitcnt lgkmcnt(0)
; DI void attn_pass_da(const bfr* __restrict__ P, int b, int tq_wave, int qcol, int kcol, int vcol, int key0, int nkt, char* smem, f32x16 (&o0)[2], f32x16 (&o1)[2]) {
;     ...
;     float mx0 = s0[0][0], mx1 = s1[0][0];
; #pragma unroll
;     for (int i = 0; i < 16; ++i) { mx0 = fmaxf(mx0, fmaxf(s0[0][i], s0[1][i])); mx1 = fmaxf(mx1, fmaxf(s1[0][i], s1[1][i])); }
;     mx0 = fmaxf(mx0, __shfl_xor(mx0, 32)); mx1 = fmaxf(mx1, __shfl_xor(mx1, 32));
;     const float mn0 = fmaxf(m0, mx0), mn1 = fmaxf(m1, mx1);
;     const float al0 = __builtin_amdgcn_exp2f(m0 - mn0), al1 = __builtin_amdgcn_exp2f(m1 - mn1);
;     m0 = mn0; m1 = mn1;
;     float ps0 = 0.f, ps1 = 0.f;
; #pragma unroll
;     for (int i = 0; i < 16; ++i) {
;       s0[0][i] = __builtin_amdgcn_exp2f(s0[0][i] - mn0); ps0 += s0[0][i];
;       s0[1][i] = __builtin_amdgcn_exp2f(s0[1][i] - mn0); ps0 += s0[1][i];
;       s1[0][i] = __builtin_amdgcn_exp2f(s1[0][i] - mn1); ps1 += s1[0][i];
;       s1[1][i] = __builtin_amdgcn_exp2f(s1[1][i] - mn1); ps1 += s1[1][i];
;     }
;     l0 = l0 * al0 + ps0; l1 = l1 * al1 + ps1;
; #pragma unroll
;     for (int i = 0; i < 16; ++i) { acc0[0][i] *= al0; acc0[1][i] *= al0; acc1[0][i] *= al1; acc1[1][i] *= al1; }
	v_mfma_f32_32x32x16_bf16 v[96:111], v[140:143], v[132:135], v[96:111]
	v_max_f32_e32 v134, v82, v82
	v_max_f32_e32 v135, v67, v67
	v_cvt_i32_f32_e32 v132, v151
	v_cndmask_b32_e32 v133, 0, v148, vcc
	v_cmp_nlt_f32_e32 vcc, s10, v146
	v_ldexp_f32 v132, v150, v132
	v_mfma_f32_32x32x16_bf16 v[112:127], v[136:139], v[128:131], v[112:127]
	s_nop 4
	v_max_f32_e32 v128, v97, v97
	v_max_f32_e32 v129, v65, v65
	v_max_f32_e32 v128, v129, v128
	v_max_f32_e32 v130, v81, v81
	v_max_f32_e32 v131, v66, v66
	v_max3_f32 v128, v64, v96, v128
	v_cndmask_b32_e32 v133, v201, v133, vcc
	v_max_f32_e32 v129, v113, v113
	v_max_f32_e32 v129, v130, v129
	v_max_f32_e32 v130, v98, v98
	v_max_f32_e32 v130, v131, v130
	v_max_f32_e32 v131, v114, v114
	v_max_f32_e32 v131, v134, v131
	v_max_f32_e32 v134, v99, v99
	v_max_f32_e32 v134, v135, v134
	v_max3_f32 v128, v128, v130, v134
	v_max_f32_e32 v130, v115, v115
	v_max_f32_e32 v134, v83, v83
	v_max3_f32 v129, v80, v112, v129
	v_max_f32_e32 v130, v134, v130
	v_max3_f32 v129, v129, v131, v130
	v_max_f32_e32 v130, v100, v100
	v_max_f32_e32 v131, v68, v68
	v_max_f32_e32 v130, v131, v130
	v_max_f32_e32 v131, v116, v116
	v_max_f32_e32 v134, v84, v84
	v_max_f32_e32 v131, v134, v131
	v_max_f32_e32 v134, v101, v101
	v_max_f32_e32 v135, v69, v69
	v_max_f32_e32 v134, v135, v134
	v_max3_f32 v128, v128, v130, v134
	v_max_f32_e32 v130, v117, v117
	v_max_f32_e32 v134, v85, v85
	v_max_f32_e32 v130, v134, v130
	v_max3_f32 v129, v129, v131, v130
	v_max_f32_e32 v130, v102, v102
	v_max_f32_e32 v131, v70, v70
	v_max_f32_e32 v130, v131, v130
	v_max_f32_e32 v131, v118, v118
	v_max_f32_e32 v134, v86, v86
	v_max_f32_e32 v131, v134, v131
	v_max_f32_e32 v134, v103, v103
	v_max_f32_e32 v135, v71, v71
	v_max_f32_e32 v134, v135, v134
	v_max3_f32 v128, v128, v130, v134
	v_max_f32_e32 v130, v119, v119
	v_max_f32_e32 v134, v87, v87
	v_max_f32_e32 v130, v134, v130
	v_max3_f32 v129, v129, v131, v130
	v_max_f32_e32 v130, v104, v104
	v_max_f32_e32 v131, v72, v72
	v_max_f32_e32 v130, v131, v130
	v_max_f32_e32 v131, v120, v120
	v_max_f32_e32 v134, v88, v88
	v_max_f32_e32 v131, v134, v131
	v_max_f32_e32 v134, v105, v105
	v_max_f32_e32 v135, v73, v73
	v_max_f32_e32 v134, v135, v134
	v_max3_f32 v128, v128, v130, v134
	v_max_f32_e32 v130, v121, v121
	v_max_f32_e32 v134, v89, v89
	v_max_f32_e32 v130, v134, v130
	v_max3_f32 v129, v129, v131, v130
	v_max_f32_e32 v130, v106, v106
	v_max_f32_e32 v131, v74, v74
	v_max_f32_e32 v130, v131, v130
	v_max_f32_e32 v131, v122, v122
	v_max_f32_e32 v134, v90, v90
	v_max_f32_e32 v131, v134, v131
	v_max_f32_e32 v134, v107, v107
	v_max_f32_e32 v135, v75, v75
	v_max_f32_e32 v134, v135, v134
	v_max3_f32 v128, v128, v130, v134
	v_max_f32_e32 v130, v123, v123
	v_max_f32_e32 v134, v91, v91
	v_max_f32_e32 v130, v134, v130
	v_max3_f32 v129, v129, v131, v130
	v_max_f32_e32 v130, v108, v108
	v_max_f32_e32 v131, v76, v76
	v_max_f32_e32 v130, v131, v130
	v_max_f32_e32 v131, v124, v124
	v_max_f32_e32 v134, v92, v92
	v_max_f32_e32 v131, v134, v131
	v_max_f32_e32 v134, v109, v109
	v_max_f32_e32 v135, v77, v77
	v_max_f32_e32 v134, v135, v134
	v_max3_f32 v128, v128, v130, v134
	v_max_f32_e32 v130, v125, v125
	v_max_f32_e32 v134, v93, v93
	v_max_f32_e32 v130, v134, v130
	v_max3_f32 v129, v129, v131, v130
	v_max_f32_e32 v130, v110, v110
	v_max_f32_e32 v131, v78, v78
	v_max_f32_e32 v130, v131, v130
	v_max_f32_e32 v131, v126, v126
	v_max_f32_e32 v134, v94, v94
	v_max_f32_e32 v131, v134, v131
	v_max_f32_e32 v134, v111, v111
	v_max_f32_e32 v135, v79, v79
	v_max_f32_e32 v134, v135, v134
	v_max3_f32 v128, v128, v130, v134
	v_max_f32_e32 v130, v127, v127
	v_max_f32_e32 v134, v95, v95
	v_max_f32_e32 v130, v134, v130
	v_max3_f32 v130, v129, v131, v130
	ds_bpermute_b32 v131, v166, v128
	ds_bpermute_b32 v134, v166, v130
	v_cmp_ngt_f32_e32 vcc, s15, v149
	s_waitcnt lgkmcnt(0)
	v_max3_f32 v150, v210, v130, v134
	v_cndmask_b32_e32 v132, 0, v132, vcc
	v_cmp_nlt_f32_e32 vcc, s10, v149
	v_max3_f32 v149, v209, v128, v131
	v_sub_f32_e32 v64, v64, v149
	v_exp_f32_e32 v148, v64
	v_sub_f32_e32 v64, v96, v149
	v_exp_f32_e32 v131, v64
	v_sub_f32_e32 v64, v80, v150
	v_exp_f32_e32 v151, v64
	v_sub_f32_e32 v64, v112, v150
	v_exp_f32_e32 v96, v64
	v_sub_f32_e32 v64, v65, v149
	v_exp_f32_e32 v152, v64
	v_sub_f32_e32 v64, v97, v149
	v_exp_f32_e32 v112, v64
	v_sub_f32_e32 v64, v81, v150
	v_exp_f32_e32 v158, v64
	v_sub_f32_e32 v64, v113, v150
	v_exp_f32_e32 v97, v64
	v_sub_f32_e32 v64, v66, v149
	v_exp_f32_e32 v143, v64
	v_sub_f32_e32 v64, v98, v149
	v_exp_f32_e32 v113, v64
	v_sub_f32_e32 v64, v82, v150
	v_exp_f32_e32 v146, v64
	v_sub_f32_e32 v64, v114, v150
	v_exp_f32_e32 v98, v64
	v_sub_f32_e32 v64, v67, v149
	v_exp_f32_e32 v147, v64
	v_sub_f32_e32 v64, v99, v149
	v_exp_f32_e32 v114, v64
	v_sub_f32_e32 v64, v83, v150
	v_exp_f32_e32 v138, v64
	v_sub_f32_e32 v64, v115, v150
	v_exp_f32_e32 v99, v64
	v_sub_f32_e32 v64, v68, v149
	v_exp_f32_e32 v139, v64
	v_sub_f32_e32 v64, v100, v149
	v_exp_f32_e32 v115, v64
	v_sub_f32_e32 v64, v84, v150
	v_exp_f32_e32 v140, v64
	v_sub_f32_e32 v64, v116, v150
	v_exp_f32_e32 v100, v64
	v_sub_f32_e32 v64, v69, v149
	v_exp_f32_e32 v141, v64
	v_sub_f32_e32 v64, v101, v149
	v_exp_f32_e32 v116, v64
	v_sub_f32_e32 v64, v85, v150
	v_exp_f32_e32 v142, v64
	v_sub_f32_e32 v64, v117, v150
	v_exp_f32_e32 v101, v64
	v_sub_f32_e32 v64, v70, v149
	v_exp_f32_e32 v134, v64
	v_sub_f32_e32 v64, v102, v149
	v_cndmask_b32_e32 v129, v201, v132, vcc
	v_exp_f32_e32 v132, v64
	v_sub_f32_e32 v64, v86, v150
	v_exp_f32_e32 v135, v64
	v_sub_f32_e32 v64, v118, v150
	v_exp_f32_e32 v117, v64
	v_sub_f32_e32 v64, v71, v149
	v_exp_f32_e32 v136, v64
	v_sub_f32_e32 v64, v103, v149
; #define MFMA32(a, b, c) __builtin_amdgcn_mfma_f32_32x32x16_bf16((a), (b), (c), 0, 0, 0)
; DI unsigned pack2(float a, float b) { unsigned r; asm volatile("v_cvt_pk_bf16_f32 %0, %1, %2" : "=v"(r) : "v"(a), "v"(b)); return r; }
; DI void attn_pass_da(const bfr* __restrict__ P, int b, int tq_wave, int qcol, int kcol, int vcol, int key0, int nkt, char* smem, f32x16 (&o0)[2], f32x16 (&o1)[2]) {
;     ...
;     for (int i = 0; i < 16; ++i) {
;       s0[0][i] = __builtin_amdgcn_exp2f(s0[0][i] - mn0); ps0 += s0[0][i];
;       s0[1][i] = __builtin_amdgcn_exp2f(s0[1][i] - mn0); ps0 += s0[1][i];
;       s1[0][i] = __builtin_amdgcn_exp2f(s1[0][i] - mn1); ps1 += s1[0][i];
;       s1[1][i] = __builtin_amdgcn_exp2f(s1[1][i] - mn1); ps1 += s1[1][i];
;     }
;     l0 = l0 * al0 + ps0; l1 = l1 * al1 + ps1;
; #pragma unroll
;     for (int i = 0; i < 16; ++i) { acc0[0][i] *= al0; acc0[1][i] *= al0; acc1[0][i] *= al1; acc1[1][i] *= al1; }
; #pragma unroll
;     for (int t2 = 0; t2 < 2; ++t2)
; #pragma unroll
;       for (int j = 0; j < 2; ++j) {
;         u32x4 pk0, pk1;
;         pk0.x = pack2(s0[t2][8 * j + 0], s0[t2][8 * j + 1]); pk0.y = pack2(s0[t2][8 * j + 2], s0[t2][8 * j + 3]);
;         pk0.z = pack2(s0[t2][8 * j + 4], s0[t2][8 * j + 5]); pk0.w = pack2(s0[t2][8 * j + 6], s0[t2][8 * j + 7]);
;         pk1.x = pack2(s1[t2][8 * j + 0], s1[t2][8 * j + 1]); pk1.y = pack2(s1[t2][8 * j + 2], s1[t2][8 * j + 3]);
;         pk1.z = pack2(s1[t2][8 * j + 4], s1[t2][8 * j + 5]); pk1.w = pack2(s1[t2][8 * j + 6], s1[t2][8 * j + 7]);
;         const bf16x8 pf0 = __builtin_bit_cast(bf16x8, pk0), pf1 = __builtin_bit_cast(bf16x8, pk1);
; #pragma unroll
;         for (int dt = 0; dt < 2; ++dt) {
;           const int vsw = (((dt * 32 + r) >> 3) & 7) << 3;
;           const bfr* vrow = sV + (dt * 32 + r) * 72;
;           s16x4 lo = *(const s16x4*)(vrow + ((t2 * 32 + 16 * j + 4 * h) ^ vsw));
;           s16x4 hi = *(const s16x4*)(vrow + ((t2 * 32 + 16 * j + 4 * h + 8) ^ vsw));
;           bf16x8 vf = __builtin_shufflevector(lo, hi, 0, 1, 2, 3, 4, 5, 6, 7);
;           acc0[dt] = MFMA32(vf, pf0, acc0[dt]);
;           acc1[dt] = MFMA32(vf, pf1, acc1[dt]);
;         }
;       }
	v_sub_f32_e32 v129, v133, v129
	v_exp_f32_e32 v133, v64
	v_sub_f32_e32 v64, v87, v150
	v_exp_f32_e32 v137, v64
	v_sub_f32_e32 v64, v119, v150
	v_exp_f32_e32 v102, v64
	v_sub_f32_e32 v64, v72, v149
	v_exp_f32_e32 v103, v64
	v_sub_f32_e32 v64, v104, v149
	v_exp_f32_e32 v71, v64
	v_sub_f32_e32 v64, v88, v150
	v_exp_f32_e32 v104, v64
	v_sub_f32_e32 v64, v120, v150
	v_exp_f32_e32 v70, v64
	v_sub_f32_e32 v64, v73, v149
	v_exp_f32_e32 v118, v64
	v_sub_f32_e32 v64, v105, v149
	v_exp_f32_e32 v73, v64
	v_sub_f32_e32 v64, v89, v150
	v_exp_f32_e32 v105, v64
	v_sub_f32_e32 v64, v121, v150
	v_exp_f32_e32 v72, v64
	v_sub_f32_e32 v64, v74, v149
	v_exp_f32_e32 v119, v64
	v_sub_f32_e32 v64, v106, v149
	v_exp_f32_e32 v81, v64
	v_sub_f32_e32 v64, v90, v150
	v_exp_f32_e32 v89, v64
	v_sub_f32_e32 v64, v122, v150
	v_exp_f32_e32 v80, v64
	v_sub_f32_e32 v64, v75, v149
	v_exp_f32_e32 v90, v64
	v_sub_f32_e32 v64, v107, v149
	v_exp_f32_e32 v87, v64
	v_sub_f32_e32 v64, v91, v150
	v_exp_f32_e32 v91, v64
	v_sub_f32_e32 v64, v123, v150
	v_exp_f32_e32 v86, v64
	v_sub_f32_e32 v64, v76, v149
	v_exp_f32_e32 v74, v64
	v_sub_f32_e32 v64, v108, v149
	v_exp_f32_e32 v75, v64
	v_sub_f32_e32 v64, v92, v150
	v_exp_f32_e32 v76, v64
	v_sub_f32_e32 v64, v124, v150
	v_exp_f32_e32 v82, v64
	v_sub_f32_e32 v64, v77, v149
	v_exp_f32_e32 v77, v64
	v_sub_f32_e32 v64, v109, v149
	v_exp_f32_e32 v83, v64
	v_sub_f32_e32 v64, v93, v150
	v_exp_f32_e32 v84, v64
	v_sub_f32_e32 v64, v125, v150
	v_exp_f32_e32 v85, v64
	v_sub_f32_e32 v64, v78, v149
	v_exp_f32_e32 v78, v64
	v_sub_f32_e32 v64, v110, v149
	v_exp_f32_e32 v88, v64
	v_sub_f32_e32 v64, v94, v150
	v_exp_f32_e32 v66, v64
	v_sub_f32_e32 v64, v126, v150
	v_exp_f32_e32 v67, v64
	v_sub_f32_e32 v64, v79, v149
	v_exp_f32_e32 v68, v64
	v_sub_f32_e32 v64, v111, v149
	v_lshl_add_u32 v79, v181, 1, v144
	v_lshl_add_u32 v110, v180, 1, v144
	v_lshl_add_u32 v124, v179, 1, v145
	v_lshl_add_u32 v126, v178, 1, v145
	v_exp_f32_e32 v69, v64
	v_sub_f32_e32 v64, v95, v150
	v_sub_f32_e32 v65, v127, v150
	v_cvt_pk_bf16_f32 v92, v148, v152
	v_cvt_pk_bf16_f32 v93, v143, v147
	v_cvt_pk_bf16_f32 v94, v139, v141
	v_cvt_pk_bf16_f32 v95, v134, v136
	v_cvt_pk_bf16_f32 v106, v151, v158
	v_cvt_pk_bf16_f32 v107, v146, v138
	v_cvt_pk_bf16_f32 v108, v140, v142
	v_cvt_pk_bf16_f32 v109, v135, v137
	ds_read_b64 v[120:121], v79 offset:27648
	ds_read_b64 v[122:123], v110 offset:27648
	ds_read_b64 v[124:125], v124 offset:27648
	ds_read_b64 v[126:127], v126 offset:27648
	v_sub_f32_e32 v128, v209, v149
	v_exp_f32_e32 v130, v128
	v_sub_f32_e32 v128, v210, v150
	v_add_f32_e32 v111, 0, v151
	v_exp_f32_e32 v128, v128
	v_add_f32_e32 v110, 0, v148
	v_add_f32_e32 v111, v96, v111
	v_add_f32_e32 v110, v131, v110
	v_add_f32_e32 v111, v158, v111
	v_add_f32_e32 v110, v152, v110
	v_add_f32_e32 v111, v97, v111
	v_add_f32_e32 v110, v112, v110
	v_add_f32_e32 v111, v146, v111
	v_pk_mul_f32 v[46:47], v[46:47], v[128:129] op_sel_hi:[1,0]
	v_pk_mul_f32 v[44:45], v[44:45], v[128:129] op_sel_hi:[1,0]
	v_pk_mul_f32 v[42:43], v[42:43], v[128:129] op_sel_hi:[1,0]
	v_pk_mul_f32 v[40:41], v[40:41], v[128:129] op_sel_hi:[1,0]
	v_pk_mul_f32 v[38:39], v[38:39], v[128:129] op_sel_hi:[1,0]
	v_pk_mul_f32 v[36:37], v[36:37], v[128:129] op_sel_hi:[1,0]
	v_pk_mul_f32 v[34:35], v[34:35], v[128:129] op_sel_hi:[1,0]
	v_pk_mul_f32 v[32:33], v[32:33], v[128:129] op_sel_hi:[1,0]
	v_pk_mul_f32 v[14:15], v[14:15], v[128:129] op_sel_hi:[1,0]
	v_pk_mul_f32 v[12:13], v[12:13], v[128:129] op_sel_hi:[1,0]
	v_pk_mul_f32 v[10:11], v[10:11], v[128:129] op_sel_hi:[1,0]
	v_pk_mul_f32 v[8:9], v[8:9], v[128:129] op_sel_hi:[1,0]
	v_pk_mul_f32 v[6:7], v[6:7], v[128:129] op_sel_hi:[1,0]
	v_pk_mul_f32 v[4:5], v[4:5], v[128:129] op_sel_hi:[1,0]
	v_pk_mul_f32 v[2:3], v[2:3], v[128:129] op_sel_hi:[1,0]
	v_pk_mul_f32 v[0:1], v[0:1], v[128:129] op_sel_hi:[1,0]
	v_add_f32_e32 v110, v143, v110
	v_add_f32_e32 v111, v98, v111
	s_waitcnt lgkmcnt(2)
	v_mfma_f32_32x32x16_bf16 v[32:47], v[120:123], v[106:109], v[32:47]
	v_add_f32_e32 v110, v113, v110
	v_add_f32_e32 v110, v147, v110
	v_add_f32_e32 v110, v114, v110
	v_mul_f32_e64 v62, v62, v130
	v_mul_f32_e64 v63, v63, v130
	v_pk_mul_f32 v[60:61], v[60:61], v[130:131] op_sel_hi:[1,0]
	v_pk_mul_f32 v[58:59], v[58:59], v[130:131] op_sel_hi:[1,0]
	v_pk_mul_f32 v[56:57], v[56:57], v[130:131] op_sel_hi:[1,0]
	s_waitcnt lgkmcnt(0)
	v_mfma_f32_32x32x16_bf16 v[0:15], v[124:127], v[106:109], v[0:15]
	v_add_f32_e32 v106, v138, v111
	v_add_f32_e32 v106, v99, v106
	v_add_f32_e32 v106, v140, v106
	v_add_f32_e32 v107, v139, v110
	v_add_f32_e32 v106, v100, v106
	v_add_f32_e32 v107, v115, v107
	v_add_f32_e32 v106, v142, v106
	v_pk_mul_f32 v[54:55], v[54:55], v[130:131] op_sel_hi:[1,0]
	v_pk_mul_f32 v[52:53], v[52:53], v[130:131] op_sel_hi:[1,0]
	v_pk_mul_f32 v[50:51], v[50:51], v[130:131] op_sel_hi:[1,0]
	v_pk_mul_f32 v[48:49], v[48:49], v[130:131] op_sel_hi:[1,0]
	v_pk_mul_f32 v[30:31], v[30:31], v[130:131] op_sel_hi:[1,0]
	v_pk_mul_f32 v[28:29], v[28:29], v[130:131] op_sel_hi:[1,0]
	v_pk_mul_f32 v[26:27], v[26:27], v[130:131] op_sel_hi:[1,0]
	v_pk_mul_f32 v[24:25], v[24:25], v[130:131] op_sel_hi:[1,0]
	v_pk_mul_f32 v[22:23], v[22:23], v[130:131] op_sel_hi:[1,0]
	v_pk_mul_f32 v[20:21], v[20:21], v[130:131] op_sel_hi:[1,0]
	v_pk_mul_f32 v[18:19], v[18:19], v[130:131] op_sel_hi:[1,0]
	v_pk_mul_f32 v[16:17], v[16:17], v[130:131] op_sel_hi:[1,0]
	v_lshl_add_u32 v143, v177, 1, v144
	v_add_f32_e32 v107, v141, v107
	v_add_f32_e32 v111, v101, v106
	v_lshl_add_u32 v106, v175, 1, v145
	v_lshl_add_u32 v108, v174, 1, v145
	v_exp_f32_e32 v64, v64
	v_mfma_f32_32x32x16_bf16 v[48:63], v[120:123], v[92:95], v[48:63]
	v_add_f32_e32 v110, v116, v107
	v_add_f32_e32 v110, v134, v110
	v_add_f32_e32 v110, v132, v110
	v_add_f32_e32 v110, v136, v110
	v_add_f32_e32 v111, v135, v111
	v_add_f32_e32 v111, v117, v111
	v_exp_f32_e32 v65, v65
	v_mfma_f32_32x32x16_bf16 v[16:31], v[124:127], v[92:95], v[16:31]
	v_cvt_pk_bf16_f32 v92, v103, v118
	v_cvt_pk_bf16_f32 v93, v119, v90
	v_cvt_pk_bf16_f32 v94, v74, v77
	v_cvt_pk_bf16_f32 v95, v78, v68
	v_cvt_pk_bf16_f32 v120, v104, v105
	v_cvt_pk_bf16_f32 v121, v89, v91
	v_cvt_pk_bf16_f32 v122, v76, v84
	v_cvt_pk_bf16_f32 v123, v66, v64
	ds_read_b64 v[146:147], v143 offset:27648
	ds_read_b64 v[106:107], v106 offset:27648
	ds_read_b64 v[108:109], v108 offset:27648
	v_lshl_add_u32 v143, v176, 1, v144
	ds_read_b64 v[148:149], v143 offset:27648
	v_add_f32_e32 v124, v133, v110
	s_waitcnt lgkmcnt(0)
; DI int vhalf() { int h = __builtin_amdgcn_readfirstlane(threadIdx.x >> 8); asm volatile("" : "+s"(h)); return h; }
; #define MFMA32(a, b, c) __builtin_amdgcn_mfma_f32_32x32x16_bf16((a), (b), (c), 0, 0, 0)
; DI void attn_pass_da(const bfr* __restrict__ P, int b, int tq_wave, int qcol, int kcol, int vcol, int key0, int nkt, char* smem, f32x16 (&o0)[2], f32x16 (&o1)[2]) {
;     ...
;           acc0[dt] = MFMA32(vf, pf0, acc0[dt]);
;           acc1[dt] = MFMA32(vf, pf1, acc1[dt]);
;         }
;       }
;   }
;   l0 += __shfl_xor(l0, 32); l1 += __shfl_xor(l1, 32);
;   const float i0 = 1.f / l0, i1 = 1.f / l1;
; #pragma unroll
;   for (int i = 0; i < 16; ++i) { o0[0][i] = acc0[0][i] * i0; o0[1][i] = acc0[1][i] * i0; o1[0][i] = acc1[0][i] * i1; o1[1][i] = acc1[1][i] * i1; }
; DN void da_item(const Params& p, int l, int b, int hd, int tq0, int key0, int nkt, char* smem) {
;     ...
;   float lam = expf(d01) - expf(d23) + lam_init;
;   f32x16 o0[2], o1[2];
;   int tqw = tq0 + vhalf() * 128 + w * 32;
;   attn_pass_da(P, b, tqw, 1152 + hd * 64, 1408 + hd * 64, 1664 + hd * 64, key0, nkt, smem, o0, o1);
;   float ss = 0.f;
; #pragma unroll
;   for (int dt = 0; dt < 2; ++dt)
; #pragma unroll
;     for (int i = 0; i < 16; ++i) { float v = o0[dt][i] - lam * o1[dt][i]; o0[dt][i] = v; ss += v * v; }
	v_mfma_f32_32x32x16_bf16 v[48:63], v[146:149], v[92:95], v[48:63]
	v_add_f32_e32 v125, v137, v111
	v_lshlrev_b32_e32 v152, 1, v154
	v_mfma_f32_32x32x16_bf16 v[16:31], v[106:109], v[92:95], v[16:31]
	v_cvt_pk_bf16_f32 v92, v131, v112
	v_cvt_pk_bf16_f32 v93, v113, v114
	v_cvt_pk_bf16_f32 v94, v115, v116
	v_cvt_pk_bf16_f32 v95, v132, v133
	v_cvt_pk_bf16_f32 v96, v96, v97
	v_cvt_pk_bf16_f32 v97, v98, v99
	v_cvt_pk_bf16_f32 v98, v100, v101
	v_add_f32_e32 v100, v103, v124
	v_add_f32_e32 v100, v71, v100
	v_cvt_pk_bf16_f32 v99, v117, v102
	ds_read_b64 v[110:111], v79 offset:27712
	v_lshl_add_u32 v79, v173, 1, v144
	v_add_f32_e32 v100, v118, v100
	ds_read_b64 v[112:113], v79 offset:27648
	v_add_f32_e32 v79, v102, v125
	v_add_f32_e32 v100, v73, v100
	v_add_f32_e32 v79, v104, v79
	v_add_f32_e32 v104, v119, v100
	v_lshl_add_u32 v100, v172, 1, v145
	v_lshl_add_u32 v102, v171, 1, v145
	ds_read_b64 v[100:101], v100 offset:27648
	ds_read_b64 v[102:103], v102 offset:27648
	v_add_f32_e32 v79, v70, v79
	v_add_f32_e32 v79, v105, v79
	v_add_f32_e32 v79, v72, v79
	v_add_f32_e32 v104, v81, v104
	v_add_f32_e32 v79, v89, v79
	v_add_f32_e32 v79, v80, v79
	v_add_f32_e32 v89, v90, v104
	v_add_f32_e32 v89, v87, v89
	v_add_f32_e32 v79, v91, v79
	v_add_f32_e32 v79, v86, v79
	v_add_f32_e32 v74, v74, v89
	s_waitcnt lgkmcnt(2)
	v_mfma_f32_32x32x16_bf16 v[48:63], v[110:113], v[92:95], v[48:63]
	v_cvt_pk_bf16_f32 v90, v71, v73
	v_cvt_pk_bf16_f32 v91, v81, v87
	v_add_f32_e32 v74, v75, v74
	v_add_f32_e32 v74, v77, v74
	v_add_f32_e32 v74, v83, v74
	v_add_f32_e32 v74, v78, v74
	v_add_f32_e32 v78, v88, v74
	s_waitcnt lgkmcnt(0)
	v_mfma_f32_32x32x16_bf16 v[16:31], v[100:103], v[92:95], v[16:31]
	v_cvt_pk_bf16_f32 v92, v75, v83
	v_add_f32_e32 v75, v76, v79
	v_add_f32_e32 v75, v82, v75
	v_add_f32_e32 v75, v84, v75
	v_add_f32_e32 v79, v85, v75
	v_add_f32_e32 v66, v66, v79
	v_cvt_pk_bf16_f32 v93, v88, v69
	v_mfma_f32_32x32x16_bf16 v[32:47], v[146:149], v[120:123], v[32:47]
	v_cvt_pk_bf16_f32 v70, v70, v72
	v_cvt_pk_bf16_f32 v71, v80, v86
	v_cvt_pk_bf16_f32 v72, v82, v85
	v_cvt_pk_bf16_f32 v73, v67, v65
	v_add_f32_e32 v66, v67, v66
	v_add_f32_e32 v67, v68, v78
	v_add_f32_e32 v67, v69, v67
	v_mfma_f32_32x32x16_bf16 v[0:15], v[106:109], v[120:123], v[0:15]
	v_fmac_f32_e32 v67, v156, v130
	ds_bpermute_b32 v68, v166, v67
	v_lshl_add_u32 v80, v169, 1, v144
	v_lshl_add_u32 v74, v168, 1, v145
	v_lshl_add_u32 v76, v167, 1, v145
	ds_read_b64 v[104:105], v80 offset:27648
	ds_read_b64 v[74:75], v74 offset:27648
	ds_read_b64 v[76:77], v76 offset:27648
	v_lshl_add_u32 v80, v170, 1, v144
	v_add_f32_e32 v64, v64, v66
	ds_read_b64 v[106:107], v80 offset:27648
	v_add_f32_e32 v65, v65, v64
	v_mfma_f32_32x32x16_bf16 v[32:47], v[110:113], v[96:99], v[32:47]
	v_fmac_f32_e32 v65, v157, v128
	s_waitcnt lgkmcnt(4)
	v_add_f32_e32 v66, v67, v68
	ds_bpermute_b32 v67, v166, v65
	v_div_scale_f32 v68, s[10:11], v66, v66, 1.0
	v_rcp_f32_e32 v69, v68
	v_add_f32_e32 v64, v155, v129
	v_mfma_f32_32x32x16_bf16 v[0:15], v[100:103], v[96:99], v[0:15]
	s_waitcnt lgkmcnt(0)
	v_add_f32_e32 v65, v65, v67
	v_fma_f32 v67, -v68, v69, 1.0
	v_fmac_f32_e32 v69, v67, v69
	v_div_scale_f32 v67, vcc, 1.0, v66, 1.0
	v_mfma_f32_32x32x16_bf16 v[32:47], v[104:107], v[70:73], v[32:47]
	v_mfma_f32_32x32x16_bf16 v[0:15], v[74:77], v[70:73], v[0:15]
	v_mul_f32_e32 v70, v67, v69
	v_fma_f32 v71, -v68, v70, v67
	v_fmac_f32_e32 v70, v71, v69
	v_fma_f32 v67, -v68, v70, v67
	v_div_scale_f32 v68, s[10:11], v65, v65, 1.0
	v_rcp_f32_e32 v71, v68
	v_div_fmas_f32 v67, v67, v69, v70
	v_div_fixup_f32 v66, v67, v66, 1.0
	v_mfma_f32_32x32x16_bf16 v[48:63], v[104:107], v[90:93], v[48:63]
	v_fma_f32 v67, -v68, v71, 1.0
	v_fmac_f32_e32 v71, v67, v71
	v_div_scale_f32 v67, vcc, 1.0, v65, 1.0
	v_mul_f32_e32 v69, v67, v71
	v_fma_f32 v70, -v68, v69, v67
	v_fmac_f32_e32 v69, v70, v71
	v_fma_f32 v67, -v68, v69, v67
	v_div_fmas_f32 v67, v67, v71, v69
	v_div_fixup_f32 v68, v67, v65, 1.0
	v_mul_f32_e32 v65, v0, v68
	v_mul_f32_e32 v0, v33, v68
	v_mul_f32_e32 v67, v1, v68
	v_mul_f32_e32 v1, v34, v68
	v_mul_f32_e32 v0, v64, v0
	v_mul_f32_e32 v32, v32, v68
	v_mul_f32_e32 v69, v2, v68
	v_mul_f32_e32 v2, v35, v68
	v_mul_f32_e32 v33, v37, v68
	v_mul_f32_e32 v37, v41, v68
	v_mul_f32_e32 v41, v45, v68
	v_fma_f32 v45, v49, v66, -v0
	v_mul_f32_e32 v0, v64, v1
	v_mul_f32_e32 v70, v3, v68
	v_mul_f32_e32 v3, v36, v68
	v_mul_f32_e32 v35, v39, v68
	v_mul_f32_e32 v39, v43, v68
	v_mul_f32_e32 v43, v47, v68
	v_mul_f32_e32 v32, v64, v32
	v_fma_f32 v47, v50, v66, -v0
	v_mul_f32_e32 v0, v64, v2
	v_mul_f32_e32 v36, v40, v68
	v_mul_f32_e32 v40, v44, v68
	v_fma_f32 v44, v48, v66, -v32
	v_fma_f32 v48, v51, v66, -v0
	v_mul_f32_e32 v0, v64, v3
	v_mul_f32_e32 v34, v38, v68
	v_fma_f32 v49, v52, v66, -v0
	v_mul_f32_e32 v0, v64, v33
	s_mov_b32 s10, 23
	v_fma_f32 v50, v53, v66, -v0
	v_mul_f32_e32 v0, v64, v34
	s_ashr_i32 s11, s10, 31
	v_fma_f32 v51, v54, v66, -v0
	v_mul_f32_e32 v0, v64, v35
	s_lshl_b64 s[10:11], s[10:11], 3
	v_fma_f32 v52, v55, v66, -v0
	v_mul_f32_e32 v0, v64, v36
	s_add_u32 s10, s0, s10
	v_mul_f32_e32 v38, v42, v68
	v_fma_f32 v53, v56, v66, -v0
	v_mul_f32_e32 v0, v64, v37
	s_addc_u32 s11, s1, s11
	v_fma_f32 v54, v57, v66, -v0
	v_mul_f32_e32 v0, v64, v38
	s_load_dwordx2 s[10:11], s[10:11], 0x0
	v_mul_f32_e32 v42, v46, v68
	v_mul_f32_e32 v46, v45, v45
	v_fma_f32 v55, v58, v66, -v0
	v_mul_f32_e32 v0, v64, v39
	v_fmac_f32_e32 v46, v44, v44
	v_fma_f32 v56, v59, v66, -v0
	v_mul_f32_e32 v0, v64, v40
	v_fmac_f32_e32 v46, v47, v47
	v_fma_f32 v57, v60, v66, -v0
	v_mul_f32_e32 v0, v64, v41
	v_fmac_f32_e32 v46, v48, v48
	v_fma_f32 v58, v61, v66, -v0
	s_lshl_b64 s[12:13], s[12:13], 2
	v_lshrrev_b32_e32 v0, 3, v164
	v_fmac_f32_e32 v46, v49, v49
	s_waitcnt lgkmcnt(0)
; DI int oidx(int i) { asm volatile("" : "+s"(i)); return i; }
; DI unsigned pack2(float a, float b) { unsigned r; asm volatile("v_cvt_pk_bf16_f32 %0, %1, %2" : "=v"(r) : "v"(a), "v"(b)); return r; }
; DI void store_o(bfr* O, int m, int colbase, int h, const f32x16 (&o)[2]) {
; #pragma unroll
;   for (int dt = 0; dt < 2; ++dt)
; #pragma unroll
;     for (int g4 = 0; g4 < 4; ++g4) {
;       int dv = dt * 32 + 8 * g4 + 4 * h;
;       uint2 pk; pk.x = pack2(o[dt][4 * g4], o[dt][4 * g4 + 1]); pk.y = pack2(o[dt][4 * g4 + 2], o[dt][4 * g4 + 3]);
;       *(uint2*)(O + (size_t)m * DM + colbase + dv) = pk;
;     }
; }
; DN void da_item(const Params& p, int l, int b, int hd, int tq0, int key0, int nkt, char* smem) {
;     ...
;     for (int i = 0; i < 16; ++i) { float v = o0[dt][i] - lam * o1[dt][i]; o0[dt][i] = v; ss += v * v; }
;   ss += __shfl_xor(ss, 32);
;   float rstd = rsqrtf(ss * (1.f / 64.f) + 1e-6f) * (1.f - lam_init);
;   const float* sg = p.in[oidx(23)] + l * 64;
; #pragma unroll
;   for (int dt = 0; dt < 2; ++dt)
; #pragma unroll
;     for (int i = 0; i < 16; ++i) { int dv = dt * 32 + 8 * (i >> 2) + 4 * h + (i & 3); o0[dt][i] = o0[dt][i] * rstd * sg[dv]; }
;   store_o(O, b * TT + tqw + r, 256 + hd * 64, h, o0);
	s_add_u32 s10, s10, s12
	v_and_b32_e32 v59, 4, v0
	v_fmac_f32_e32 v46, v50, v50
	s_addc_u32 s11, s11, s13
	v_lshlrev_b32_e32 v60, 2, v59
	v_mfma_f32_32x32x16_bf16 v[16:31], v[74:77], v[90:93], v[16:31]
	v_fmac_f32_e32 v46, v51, v51
	global_load_dwordx4 v[0:3], v60, s[10:11]
	v_fmac_f32_e32 v46, v52, v52
	v_fmac_f32_e32 v46, v53, v53
	v_mul_f32_e32 v32, v64, v42
	v_fmac_f32_e32 v46, v54, v54
	v_fma_f32 v61, v62, v66, -v32
	v_mul_f32_e32 v32, v64, v43
	v_fmac_f32_e32 v46, v55, v55
	v_fma_f32 v62, v63, v66, -v32
	global_load_dwordx4 v[32:35], v60, s[10:11] offset:32
	v_fmac_f32_e32 v46, v56, v56
	v_fmac_f32_e32 v46, v57, v57
	v_fmac_f32_e32 v46, v58, v58
	v_mul_f32_e32 v36, v64, v65
	v_fmac_f32_e32 v46, v61, v61
	v_fma_f32 v63, v16, v66, -v36
	v_mul_f32_e32 v16, v64, v67
	global_load_dwordx4 v[36:39], v60, s[10:11] offset:64
	v_mul_f32_e32 v4, v4, v68
	v_fmac_f32_e32 v46, v62, v62
	v_fma_f32 v65, v17, v66, -v16
	v_mul_f32_e32 v16, v64, v69
	v_mul_f32_e32 v5, v5, v68
	v_fmac_f32_e32 v46, v63, v63
	v_fma_f32 v67, v18, v66, -v16
	v_mul_f32_e32 v16, v64, v70
	v_mul_f32_e32 v4, v64, v4
	v_fmac_f32_e32 v46, v65, v65
	v_fma_f32 v69, v19, v66, -v16
	v_fma_f32 v70, v20, v66, -v4
	v_mul_f32_e32 v4, v64, v5
	v_fmac_f32_e32 v46, v67, v67
	global_load_dwordx4 v[16:19], v60, s[10:11] offset:96
	v_fma_f32 v71, v21, v66, -v4
	v_pk_mul_f32 v[4:5], v[6:7], v[68:69] op_sel_hi:[1,0]
	v_fmac_f32_e32 v46, v69, v69
	v_pk_mul_f32 v[4:5], v[64:65], v[4:5] op_sel_hi:[0,1]
	v_fmac_f32_e32 v46, v70, v70
	v_pk_fma_f32 v[40:41], v[22:23], v[66:67], v[4:5] op_sel_hi:[1,0,1] neg_lo:[0,0,1] neg_hi:[0,0,1]
	v_pk_mul_f32 v[8:9], v[8:9], v[68:69] op_sel_hi:[1,0]
	v_fmac_f32_e32 v46, v71, v71
	v_pk_mul_f32 v[20:21], v[40:41], v[40:41]
	v_pk_mul_f32 v[8:9], v[64:65], v[8:9] op_sel_hi:[0,1]
	global_load_dwordx4 v[4:7], v60, s[10:11] offset:128
	v_add_f32_e32 v20, v20, v46
	v_pk_fma_f32 v[24:25], v[24:25], v[66:67], v[8:9] op_sel_hi:[1,0,1] neg_lo:[0,0,1] neg_hi:[0,0,1]
	v_add_f32_e32 v20, v21, v20
	v_pk_mul_f32 v[8:9], v[24:25], v[24:25]
	v_pk_mul_f32 v[12:13], v[12:13], v[68:69] op_sel_hi:[1,0]
	v_add_f32_e32 v8, v8, v20
	v_add_f32_e32 v42, v9, v8
	v_pk_mul_f32 v[8:9], v[10:11], v[68:69] op_sel_hi:[1,0]
	global_load_dwordx4 v[20:23], v60, s[10:11] offset:160
	v_pk_mul_f32 v[8:9], v[64:65], v[8:9] op_sel_hi:[0,1]
	v_pk_fma_f32 v[26:27], v[26:27], v[66:67], v[8:9] op_sel_hi:[1,0,1] neg_lo:[0,0,1] neg_hi:[0,0,1]
	v_pk_mul_f32 v[12:13], v[64:65], v[12:13] op_sel_hi:[0,1]
	v_pk_mul_f32 v[8:9], v[26:27], v[26:27]
	v_pk_fma_f32 v[28:29], v[28:29], v[66:67], v[12:13] op_sel_hi:[1,0,1] neg_lo:[0,0,1] neg_hi:[0,0,1]
	v_add_f32_e32 v8, v8, v42
	v_add_f32_e32 v42, v9, v8
	global_load_dwordx4 v[8:11], v60, s[10:11] offset:192
	v_pk_mul_f32 v[12:13], v[28:29], v[28:29]
	s_load_dwordx4 s[12:15], s[0:1], 0x100
	v_add_f32_e32 v12, v12, v42
	v_add_f32_e32 v46, v13, v12
	v_pk_mul_f32 v[42:43], v[14:15], v[68:69] op_sel_hi:[1,0]
	global_load_dwordx4 v[12:15], v60, s[10:11] offset:224
	v_pk_mul_f32 v[42:43], v[64:65], v[42:43] op_sel_hi:[0,1]
	v_pk_fma_f32 v[30:31], v[30:31], v[66:67], v[42:43] op_sel_hi:[1,0,1] neg_lo:[0,0,1] neg_hi:[0,0,1]
	s_mov_b64 s[10:11], 0x2b7c300
	v_pk_mul_f32 v[42:43], v[30:31], v[30:31]
	s_nop 0
	v_add_f32_e32 v42, v42, v46
	v_add_f32_e32 v42, v43, v42
	ds_bpermute_b32 v43, v166, v42
	s_waitcnt lgkmcnt(0)
	v_add_f32_e32 v42, v42, v43
	v_fmamk_f32 v42, v42, 0x3c800000, v186
	v_cmp_gt_f32_e32 vcc, s33, v42
	v_mul_f32_e32 v43, 0x4b800000, v42
	s_nop 0
	v_cndmask_b32_e32 v42, v42, v43, vcc
	v_rsq_f32_e32 v42, v42
	s_nop 0
	v_mul_f32_e32 v43, 0x45800000, v42
	v_cndmask_b32_e32 v42, v42, v43, vcc
	v_mul_f32_e32 v42, v162, v42
	v_mul_f32_e32 v43, v44, v42
	s_waitcnt vmcnt(7)
	v_mul_f32_e32 v43, v0, v43
	v_mul_f32_e32 v0, v45, v42
	v_mul_f32_e32 v44, v1, v0
	v_mul_f32_e32 v0, v47, v42
	v_mul_f32_e32 v45, v2, v0
	v_mul_f32_e32 v0, v48, v42
	v_mul_f32_e32 v3, v3, v0
	v_mul_f32_e32 v0, v49, v42
	s_waitcnt vmcnt(6)
	v_mul_f32_e32 v32, v32, v0
	v_mul_f32_e32 v0, v50, v42
	v_mul_f32_e32 v33, v33, v0
	v_mul_f32_e32 v0, v51, v42
	v_mul_f32_e32 v34, v34, v0
	v_mul_f32_e32 v0, v52, v42
	v_mul_f32_e32 v35, v35, v0
	v_mul_f32_e32 v0, v53, v42
	s_waitcnt vmcnt(5)
	v_mul_f32_e32 v36, v36, v0
	v_mul_f32_e32 v0, v54, v42
	v_mul_f32_e32 v37, v37, v0
	v_mul_f32_e32 v0, v55, v42
	v_mul_f32_e32 v38, v38, v0
	v_mul_f32_e32 v0, v56, v42
	v_mul_f32_e32 v39, v39, v0
	v_mul_f32_e32 v0, v57, v42
	s_waitcnt vmcnt(4)
	v_mul_f32_e32 v16, v16, v0
	v_mul_f32_e32 v0, v58, v42
	v_mul_f32_e32 v17, v17, v0
	v_mul_f32_e32 v0, v61, v42
	v_mul_f32_e32 v18, v18, v0
	v_mul_f32_e32 v0, v62, v42
	v_mul_f32_e32 v19, v19, v0
	v_mul_f32_e32 v0, v63, v42
	s_waitcnt vmcnt(3)
	v_mul_f32_e32 v46, v4, v0
	v_mul_f32_e32 v0, v65, v42
	v_mul_f32_e32 v47, v5, v0
	v_mul_f32_e32 v0, v67, v42
	v_mul_f32_e32 v6, v6, v0
	v_mul_f32_e32 v0, v69, v42
	v_mul_f32_e32 v7, v7, v0
	v_mul_f32_e32 v0, v70, v42
	s_waitcnt vmcnt(2)
	v_mul_f32_e32 v20, v20, v0
	v_mul_f32_e32 v0, v71, v42
	v_mul_f32_e32 v21, v21, v0
	v_mul_f32_e32 v0, v40, v42
	v_mul_f32_e32 v22, v22, v0
	v_mul_f32_e32 v0, v41, v42
	v_mul_f32_e32 v23, v23, v0
	v_mul_f32_e32 v0, v24, v42
	s_waitcnt vmcnt(1)
	v_mul_f32_e32 v8, v8, v0
	v_mul_f32_e32 v0, v25, v42
	v_mul_f32_e32 v9, v9, v0
	v_mul_f32_e32 v0, v26, v42
	v_mul_f32_e32 v10, v10, v0
	v_mul_f32_e32 v0, v27, v42
	v_mul_f32_e32 v11, v11, v0
	v_mul_f32_e32 v0, v28, v42
	s_waitcnt vmcnt(0)
	v_mul_f32_e32 v12, v12, v0
	v_mul_f32_e32 v0, v29, v42
	v_mul_f32_e32 v13, v13, v0
	v_mul_f32_e32 v0, v30, v42
	v_mul_f32_e32 v14, v14, v0
	v_mul_f32_e32 v0, v31, v42
	v_mul_f32_e32 v15, v15, v0
	v_and_or_b32 v0, v164, 31, v165
	v_ashrrev_i32_e32 v1, 31, v0
	v_lshlrev_b64 v[0:1], 11, v[0:1]
	v_lshl_add_u64 v[0:1], s[14:15], 0, v[0:1]
	v_lshl_add_u64 v[0:1], v[0:1], 0, v[152:153]
	v_lshlrev_b32_e32 v152, 1, v59
	v_lshl_add_u64 v[0:1], v[0:1], 0, v[152:153]
	v_lshl_add_u64 v[4:5], v[0:1], 0, s[10:11]
	s_mov_b32 s10, 0x2b7c000
	v_add_co_u32_e32 v0, vcc, s10, v0
	v_cvt_pk_bf16_f32 v2, v43, v44
	v_cvt_pk_bf16_f32 v3, v45, v3
	s_nop 1
	v_addc_co_u32_e32 v1, vcc, 0, v1, vcc
	global_store_dwordx2 v[0:1], v[2:3], off offset:768
	v_cvt_pk_bf16_f32 v0, v32, v33
	v_cvt_pk_bf16_f32 v1, v34, v35
	global_store_dwordx2 v[4:5], v[0:1], off offset:16
	v_cvt_pk_bf16_f32 v0, v36, v37
	v_cvt_pk_bf16_f32 v1, v38, v39
	global_store_dwordx2 v[4:5], v[0:1], off offset:32
	v_cvt_pk_bf16_f32 v0, v16, v17
	v_cvt_pk_bf16_f32 v1, v18, v19
	global_store_dwordx2 v[4:5], v[0:1], off offset:48
	v_cvt_pk_bf16_f32 v0, v46, v47
	v_cvt_pk_bf16_f32 v1, v6, v7
	global_store_dwordx2 v[4:5], v[0:1], off offset:64
	v_cvt_pk_bf16_f32 v0, v20, v21
	v_cvt_pk_bf16_f32 v1, v22, v23
	global_store_dwordx2 v[4:5], v[0:1], off offset:80
	v_cvt_pk_bf16_f32 v0, v8, v9
	v_cvt_pk_bf16_f32 v1, v10, v11
	global_store_dwordx2 v[4:5], v[0:1], off offset:96
	v_cvt_pk_bf16_f32 v0, v12, v13
	v_cvt_pk_bf16_f32 v1, v14, v15
	global_store_dwordx2 v[4:5], v[0:1], off offset:112
	s_or_b64 exec, exec, s[8:9]

; DI void attn_pass_da(const bfr* __restrict__ P, int b, int tq_wave, int qcol, int kcol, int vcol, int key0, int nkt, char* smem, f32x16 (&o0)[2], f32x16 (&o1)[2]) {
;     ...
;   for (int kt = 0; kt < nkt; ++kt) {
;     bfr* sK = sbase + (kt & 1) * 9216;
;     bfr* sV = sK + 64 * 72;
;     { int c = gt, row = c >> 3, kc = c & 7; *(u32x4*)(sK + row * KP + kc * 8) = kreg[0]; }
;     for (int i = 0; i < 1; ++i) {
;       int c = gt, row = c >> 3, kc = c & 7;
;       unsigned wds[4] = {vreg[i].x, vreg[i].y, vreg[i].z, vreg[i].w};
; #pragma unroll
;       for (int e = 0; e < 4; ++e) {
;         sV[(kc * 8 + 2 * e) * 72 + (row ^ (kc << 3))] = (bfr)(wds[e] & 0xffffu);
;         sV[(kc * 8 + 2 * e + 1) * 72 + (row ^ (kc << 3))] = (bfr)(wds[e] >> 16);
;       }
;     }
;     __syncthreads();
;     if (kt + 1 < nkt) {
;       const bfr* Pn = Pb + (size_t)(kt + 1) * 64 * PW;
;       { int c = gt, row = c >> 3, kc = c & 7; kreg[0] = *(const u32x4*)(Pn + (size_t)row * PW + kcol + kc * 8); vreg[0] = *(const u32x4*)(Pn + (size_t)row * PW + vcol + kc * 8); }
;     }
;     f32x16 s0[2], s1[2];
; #pragma unroll
;     for (int t2 = 0; t2 < 2; ++t2) {
; #pragma unroll
;       for (int i = 0; i < 16; ++i) { s0[t2][i] = 0.f; s1[t2][i] = 0.f; }
; #pragma unroll
;       for (int ks = 0; ks < 2; ++ks) {
;         bf16x8 a0 = *(const bf16x8*)(sK + (t2 * 32 + r) * KP + ks * 16 + h * 8);
;         bf16x8 a1 = *(const bf16x8*)(sK + (t2 * 32 + r) * KP + 32 + ks * 16 + h * 8);
;         s0[t2] = MFMA32(a0, qf[ks], s0[t2]);
;         s1[t2] = MFMA32(a1, qf[2 + ks], s1[t2]);
;       }
;     }
;     float mx0 = s0[0][0], mx1 = s1[0][0];
; #pragma unroll
;     for (int i = 0; i < 16; ++i) { mx0 = fmaxf(mx0, fmaxf(s0[0][i], s0[1][i])); mx1 = fmaxf(mx1, fmaxf(s1[0][i], s1[1][i])); }
;     mx0 = fmaxf(mx0, __shfl_xor(mx0, 32)); mx1 = fmaxf(mx1, __shfl_xor(mx1, 32));
;     const float mn0 = fmaxf(m0, mx0), mn1 = fmaxf(m1, mx1);
;     const float al0 = __builtin_amdgcn_exp2f(m0 - mn0), al1 = __builtin_amdgcn_exp2f(m1 - mn1);
;     m0 = mn0; m1 = mn1;
;     float ps0 = 0.f, ps1 = 0.f;
; #pragma unroll
;     for (int i = 0; i < 16; ++i) {
;       s0[0][i] = __builtin_amdgcn_exp2f(s0[0][i] - mn0); ps0 += s0[0][i];
;       s0[1][i] = __builtin_amdgcn_exp2f(s0[1][i] - mn0); ps0 += s0[1][i];
;       s1[0][i] = __builtin_amdgcn_exp2f(s1[0][i] - mn1); ps1 += s1[0][i];
.LBB0_421:
	s_bitcmp1_b32 s10, 0
	s_cselect_b32 s11, 0x4800, 0
	s_add_i32 s11, s11, 0
	v_add3_u32 v64, s11, v206, v152
	v_add_u32_e32 v194, s11, v205
	s_waitcnt vmcnt(1)
	ds_write_b128 v64, v[148:151]
	v_add3_u32 v64, s11, v207, v208
	v_add3_u32 v65, s11, v208, v207
	v_add_u32_e32 v100, v194, v204
	s_waitcnt vmcnt(0)
	ds_write_b16 v64, v144 offset:9216
	ds_write_b16_d16_hi v65, v144 offset:9360
	ds_write_b16 v64, v145 offset:9504
	ds_write_b16_d16_hi v65, v145 offset:9648
	ds_write_b16 v64, v146 offset:9792
	ds_write_b16_d16_hi v65, v146 offset:9936
	ds_write_b16 v64, v147 offset:10080
	ds_write_b16_d16_hi v65, v147 offset:10224
	s_waitcnt lgkmcnt(0)
	s_barrier
	global_load_dwordx4 v[148:151], v[158:159], off
	global_load_dwordx4 v[144:147], v[158:159], off offset:512
	ds_read_b128 v[64:67], v100 offset:64
	ds_read_b128 v[68:71], v100
	ds_read_b128 v[96:99], v100 offset:32
	ds_read_b128 v[100:103], v100 offset:96
	s_waitcnt lgkmcnt(2)
	v_mfma_f32_32x32x16_bf16 v[80:95], v[68:71], v[140:143], 0
	v_add_u32_e32 v195, s11, v211
	v_add_u32_e32 v192, v195, v204
	v_mov_b32_e32 v160, v209
	v_mov_b32_e32 v161, v210
	s_add_i32 s10, s10, 1
	v_lshl_add_u64 v[158:159], v[158:159], 0, s[12:13]
	s_cmp_lg_u32 s10, 35
	v_mfma_f32_32x32x16_bf16 v[64:79], v[64:67], v[136:139], 0
	s_waitcnt lgkmcnt(1)
	v_mfma_f32_32x32x16_bf16 v[80:95], v[96:99], v[132:135], v[80:95]
	s_waitcnt lgkmcnt(0)
	v_mfma_f32_32x32x16_bf16 v[64:79], v[100:103], v[128:131], v[64:79]
	ds_read_b128 v[96:99], v192 offset:64
	ds_read_b128 v[100:103], v192
	ds_read_b128 v[212:215], v192 offset:32
	ds_read_b128 v[216:219], v192 offset:96
	s_nop 5
	v_max3_f32 v209, v80, v81, v82
	v_max3_f32 v209, v209, v83, v84
	v_max3_f32 v193, v64, v65, v66
	s_waitcnt lgkmcnt(2)
	v_mfma_f32_32x32x16_bf16 v[112:127], v[100:103], v[140:143], 0
	v_mfma_f32_32x32x16_bf16 v[96:111], v[96:99], v[136:139], 0
	s_waitcnt lgkmcnt(1)
	v_mfma_f32_32x32x16_bf16 v[112:127], v[212:215], v[132:135], v[112:127]
	v_max3_f32 v193, v193, v67, v68
	v_max3_f32 v209, v209, v85, v86
	s_waitcnt lgkmcnt(0)
	v_mfma_f32_32x32x16_bf16 v[96:111], v[216:219], v[128:131], v[96:111]
	v_max3_f32 v193, v193, v69, v70
	v_max3_f32 v209, v209, v87, v88
	v_max3_f32 v193, v193, v71, v72
	v_max3_f32 v209, v209, v89, v90
	v_max3_f32 v193, v193, v73, v74
	v_max3_f32 v209, v209, v91, v92
	v_max3_f32 v193, v193, v75, v76
	v_max3_f32 v209, v209, v93, v94
	v_max3_f32 v193, v193, v77, v78
	v_max3_f32 v209, v209, v95, v112
	v_max3_f32 v209, v209, v113, v114
	v_max3_f32 v209, v209, v115, v116
	v_max3_f32 v209, v209, v117, v118
	v_max3_f32 v209, v209, v119, v120
	v_max3_f32 v209, v209, v121, v122
	v_max3_f32 v209, v209, v123, v124
	v_max3_f32 v209, v209, v125, v126
	v_max_f32_e32 v192, v209, v127
	v_max3_f32 v193, v193, v79, v96
	v_max3_f32 v193, v193, v97, v98
	v_max3_f32 v193, v193, v99, v100
	v_max3_f32 v193, v193, v101, v102
	v_max3_f32 v193, v193, v103, v104
	v_max3_f32 v193, v193, v105, v106
	v_max3_f32 v193, v193, v107, v108
	v_max3_f32 v193, v193, v109, v110
	v_max_f32_e32 v193, v193, v111
	ds_bpermute_b32 v210, v166, v193
	ds_bpermute_b32 v209, v166, v192
	s_waitcnt lgkmcnt(1)
	v_max3_f32 v210, v161, v193, v210
	s_waitcnt lgkmcnt(0)
	v_max3_f32 v209, v160, v192, v209
	v_sub_f32_e32 v64, v64, v210
	v_sub_f32_e32 v80, v80, v209
	v_exp_f32_e32 v193, v64
	v_sub_f32_e32 v64, v96, v210
	v_exp_f32_e32 v192, v80
	v_sub_f32_e32 v80, v112, v209
	v_exp_f32_e32 v213, v64
	v_sub_f32_e32 v64, v81, v209
	v_exp_f32_e32 v212, v80
	v_exp_f32_e32 v80, v64
	v_sub_f32_e32 v64, v113, v209
	v_exp_f32_e32 v96, v64
	v_sub_f32_e32 v64, v65, v210
	v_exp_f32_e32 v81, v64
	v_sub_f32_e32 v64, v97, v210
	v_exp_f32_e32 v97, v64
	v_sub_f32_e32 v64, v82, v209
	v_exp_f32_e32 v112, v64
	v_sub_f32_e32 v64, v114, v209
	v_exp_f32_e32 v214, v64
	v_sub_f32_e32 v64, v66, v210
	v_exp_f32_e32 v113, v64
	v_sub_f32_e32 v64, v98, v210
	v_exp_f32_e32 v215, v64
	v_sub_f32_e32 v64, v83, v209
	v_exp_f32_e32 v82, v64
	v_sub_f32_e32 v64, v115, v209
	v_exp_f32_e32 v98, v64
	v_sub_f32_e32 v64, v67, v210
	v_exp_f32_e32 v83, v64
	v_sub_f32_e32 v64, v99, v210
	v_exp_f32_e32 v99, v64
	v_sub_f32_e32 v64, v84, v209
	v_exp_f32_e32 v114, v64
	v_sub_f32_e32 v64, v116, v209
	v_exp_f32_e32 v216, v64
	v_sub_f32_e32 v64, v68, v210
	v_exp_f32_e32 v115, v64
	v_sub_f32_e32 v64, v100, v210
	v_exp_f32_e32 v217, v64
	v_sub_f32_e32 v64, v85, v209
	v_exp_f32_e32 v84, v64
	v_sub_f32_e32 v64, v117, v209
	v_exp_f32_e32 v100, v64
	v_sub_f32_e32 v64, v69, v210
	v_exp_f32_e32 v85, v64
	v_sub_f32_e32 v64, v101, v210
	v_exp_f32_e32 v101, v64
	v_sub_f32_e32 v64, v86, v209
	v_exp_f32_e32 v116, v64
	v_sub_f32_e32 v64, v118, v209
	v_exp_f32_e32 v218, v64
	v_sub_f32_e32 v64, v70, v210
	v_exp_f32_e32 v117, v64
	v_sub_f32_e32 v64, v102, v210
	v_exp_f32_e32 v219, v64
	v_sub_f32_e32 v64, v87, v209
	v_exp_f32_e32 v70, v64
	v_sub_f32_e32 v64, v119, v209
	v_exp_f32_e32 v86, v64
	v_sub_f32_e32 v64, v71, v210
	v_exp_f32_e32 v71, v64
	v_sub_f32_e32 v64, v103, v210
	v_exp_f32_e32 v87, v64
	v_sub_f32_e32 v64, v88, v209
	v_exp_f32_e32 v102, v64
	v_sub_f32_e32 v64, v120, v209
	v_exp_f32_e32 v118, v64
	v_sub_f32_e32 v64, v72, v210
	v_exp_f32_e32 v103, v64
	v_sub_f32_e32 v64, v104, v210
	v_exp_f32_e32 v119, v64
	v_sub_f32_e32 v64, v89, v209
	v_exp_f32_e32 v88, v64
	v_sub_f32_e32 v64, v121, v209
	v_exp_f32_e32 v104, v64
	v_sub_f32_e32 v64, v73, v210
	v_exp_f32_e32 v89, v64
	v_sub_f32_e32 v64, v105, v210
	v_exp_f32_e32 v105, v64
	v_sub_f32_e32 v64, v90, v209
	v_exp_f32_e32 v120, v64
	v_sub_f32_e32 v64, v122, v209
	v_exp_f32_e32 v220, v64
	v_sub_f32_e32 v64, v74, v210
	v_exp_f32_e32 v121, v64
	v_sub_f32_e32 v64, v106, v210
	v_exp_f32_e32 v221, v64
; #define MFMA32(a, b, c) __builtin_amdgcn_mfma_f32_32x32x16_bf16((a), (b), (c), 0, 0, 0)
; DI unsigned pack2(float a, float b) { unsigned r; asm volatile("v_cvt_pk_bf16_f32 %0, %1, %2" : "=v"(r) : "v"(a), "v"(b)); return r; }
; DI void attn_pass_da(const bfr* __restrict__ P, int b, int tq_wave, int qcol, int kcol, int vcol, int key0, int nkt, char* smem, f32x16 (&o0)[2], f32x16 (&o1)[2]) {
;     ...
;     for (int i = 0; i < 16; ++i) {
;       s0[0][i] = __builtin_amdgcn_exp2f(s0[0][i] - mn0); ps0 += s0[0][i];
;       s0[1][i] = __builtin_amdgcn_exp2f(s0[1][i] - mn0); ps0 += s0[1][i];
;       s1[0][i] = __builtin_amdgcn_exp2f(s1[0][i] - mn1); ps1 += s1[0][i];
;       s1[1][i] = __builtin_amdgcn_exp2f(s1[1][i] - mn1); ps1 += s1[1][i];
;     }
;     l0 = l0 * al0 + ps0; l1 = l1 * al1 + ps1;
; #pragma unroll
;     for (int i = 0; i < 16; ++i) { acc0[0][i] *= al0; acc0[1][i] *= al0; acc1[0][i] *= al1; acc1[1][i] *= al1; }
; #pragma unroll
;     for (int t2 = 0; t2 < 2; ++t2)
; #pragma unroll
;       for (int j = 0; j < 2; ++j) {
;         u32x4 pk0, pk1;
;         pk0.x = pack2(s0[t2][8 * j + 0], s0[t2][8 * j + 1]); pk0.y = pack2(s0[t2][8 * j + 2], s0[t2][8 * j + 3]);
;         pk0.z = pack2(s0[t2][8 * j + 4], s0[t2][8 * j + 5]); pk0.w = pack2(s0[t2][8 * j + 6], s0[t2][8 * j + 7]);
;         pk1.x = pack2(s1[t2][8 * j + 0], s1[t2][8 * j + 1]); pk1.y = pack2(s1[t2][8 * j + 2], s1[t2][8 * j + 3]);
;         pk1.z = pack2(s1[t2][8 * j + 4], s1[t2][8 * j + 5]); pk1.w = pack2(s1[t2][8 * j + 6], s1[t2][8 * j + 7]);
;         const bf16x8 pf0 = __builtin_bit_cast(bf16x8, pk0), pf1 = __builtin_bit_cast(bf16x8, pk1);
; #pragma unroll
;         for (int dt = 0; dt < 2; ++dt) {
;           const int vsw = (((dt * 32 + r) >> 3) & 7) << 3;
;           const bfr* vrow = sV + (dt * 32 + r) * 72;
;           s16x4 lo = *(const s16x4*)(vrow + ((t2 * 32 + 16 * j + 4 * h) ^ vsw));
;           s16x4 hi = *(const s16x4*)(vrow + ((t2 * 32 + 16 * j + 4 * h + 8) ^ vsw));
;           bf16x8 vf = __builtin_shufflevector(lo, hi, 0, 1, 2, 3, 4, 5, 6, 7);
;           acc0[dt] = MFMA32(vf, pf0, acc0[dt]);
;           acc1[dt] = MFMA32(vf, pf1, acc1[dt]);
	v_sub_f32_e32 v64, v91, v209
	v_exp_f32_e32 v90, v64
	v_sub_f32_e32 v64, v123, v209
	v_exp_f32_e32 v106, v64
	v_sub_f32_e32 v64, v75, v210
	v_exp_f32_e32 v91, v64
	v_sub_f32_e32 v64, v107, v210
	v_exp_f32_e32 v107, v64
	v_sub_f32_e32 v64, v92, v209
	v_exp_f32_e32 v122, v64
	v_sub_f32_e32 v64, v124, v209
	v_exp_f32_e32 v222, v64
	v_sub_f32_e32 v64, v76, v210
	v_exp_f32_e32 v123, v64
	v_sub_f32_e32 v64, v108, v210
	v_exp_f32_e32 v223, v64
	v_sub_f32_e32 v64, v93, v209
	v_exp_f32_e32 v92, v64
	v_sub_f32_e32 v64, v125, v209
	v_exp_f32_e32 v108, v64
	v_sub_f32_e32 v64, v77, v210
	v_exp_f32_e32 v93, v64
	v_sub_f32_e32 v64, v109, v210
	v_exp_f32_e32 v109, v64
	v_sub_f32_e32 v64, v94, v209
	v_exp_f32_e32 v124, v64
	v_sub_f32_e32 v64, v126, v209
	v_exp_f32_e32 v224, v64
	v_sub_f32_e32 v64, v78, v210
	v_exp_f32_e32 v125, v64
	v_sub_f32_e32 v64, v110, v210
	v_exp_f32_e32 v225, v64
	v_sub_f32_e32 v64, v95, v209
	v_exp_f32_e32 v94, v64
	v_sub_f32_e32 v64, v127, v209
	v_exp_f32_e32 v110, v64
	v_sub_f32_e32 v64, v79, v210
	v_exp_f32_e32 v95, v64
	v_sub_f32_e32 v64, v111, v210
	v_exp_f32_e32 v111, v64
	v_pk_add_f32 v[64:65], v[192:193], 0 op_sel_hi:[1,0]
	v_sub_f32_e32 v161, v161, v210
	v_pk_add_f32 v[64:65], v[212:213], v[64:65]
	v_exp_f32_e32 v161, v161
	v_pk_add_f32 v[64:65], v[80:81], v[64:65]
	v_lshl_add_u32 v74, v180, 1, v194
	v_pk_add_f32 v[64:65], v[96:97], v[64:65]
	v_lshl_add_u32 v76, v179, 1, v195
	v_pk_add_f32 v[64:65], v[112:113], v[64:65]
	v_lshl_add_u32 v78, v178, 1, v195
	v_pk_add_f32 v[64:65], v[214:215], v[64:65]
	v_sub_f32_e32 v160, v160, v209
	v_pk_add_f32 v[64:65], v[82:83], v[64:65]
	v_exp_f32_e32 v160, v160
	v_pk_add_f32 v[64:65], v[98:99], v[64:65]
	v_pk_mul_f32 v[62:63], v[62:63], v[160:161] op_sel_hi:[1,0]
	v_pk_add_f32 v[64:65], v[114:115], v[64:65]
	v_pk_mul_f32 v[60:61], v[60:61], v[160:161] op_sel_hi:[1,0]
	v_pk_add_f32 v[64:65], v[216:217], v[64:65]
	v_pk_mul_f32 v[58:59], v[58:59], v[160:161] op_sel_hi:[1,0]
	v_pk_add_f32 v[64:65], v[84:85], v[64:65]
	v_pk_mul_f32 v[56:57], v[56:57], v[160:161] op_sel_hi:[1,0]
	v_pk_add_f32 v[64:65], v[100:101], v[64:65]
	v_pk_mul_f32 v[54:55], v[54:55], v[160:161] op_sel_hi:[1,0]
	v_pk_add_f32 v[64:65], v[116:117], v[64:65]
	v_pk_mul_f32 v[52:53], v[52:53], v[160:161] op_sel_hi:[1,0]
	v_pk_add_f32 v[64:65], v[218:219], v[64:65]
	v_pk_mul_f32 v[50:51], v[50:51], v[160:161] op_sel_hi:[1,0]
	v_pk_add_f32 v[64:65], v[70:71], v[64:65]
	v_pk_mul_f32 v[48:49], v[48:49], v[160:161] op_sel_hi:[1,0]
	v_pk_add_f32 v[64:65], v[86:87], v[64:65]
	v_pk_mul_f32 v[30:31], v[30:31], v[160:161] op_sel_hi:[1,0]
	v_pk_add_f32 v[64:65], v[102:103], v[64:65]
	v_pk_mul_f32 v[28:29], v[28:29], v[160:161] op_sel_hi:[1,0]
	v_pk_add_f32 v[64:65], v[118:119], v[64:65]
	v_pk_mul_f32 v[26:27], v[26:27], v[160:161] op_sel_hi:[1,0]
	v_pk_add_f32 v[64:65], v[88:89], v[64:65]
	v_pk_mul_f32 v[24:25], v[24:25], v[160:161] op_sel_hi:[1,0]
	v_pk_add_f32 v[64:65], v[104:105], v[64:65]
	v_pk_mul_f32 v[22:23], v[22:23], v[160:161] op_sel_hi:[1,0]
	v_pk_add_f32 v[64:65], v[120:121], v[64:65]
	v_pk_mul_f32 v[20:21], v[20:21], v[160:161] op_sel_hi:[1,0]
	v_pk_add_f32 v[126:127], v[220:221], v[64:65]
	v_cvt_pk_bf16_f32 v64, v192, v80
	v_cvt_pk_bf16_f32 v65, v112, v82
	v_lshl_add_u32 v112, v181, 1, v194
	v_cvt_pk_bf16_f32 v66, v114, v84
	v_cvt_pk_bf16_f32 v67, v116, v70
	v_cvt_pk_bf16_f32 v68, v193, v81
	v_cvt_pk_bf16_f32 v69, v113, v83
	v_cvt_pk_bf16_f32 v70, v115, v85
	v_cvt_pk_bf16_f32 v71, v117, v71
	ds_read_b64 v[72:73], v112 offset:9216
	ds_read_b64 v[74:75], v74 offset:9216
	ds_read_b64 v[76:77], v76 offset:9216
	ds_read_b64 v[78:79], v78 offset:9216
	v_mov_b32_e32 v82, v161
	v_pk_mul_f32 v[46:47], v[46:47], v[82:83] op_sel_hi:[1,0]
	v_pk_mul_f32 v[44:45], v[44:45], v[82:83] op_sel_hi:[1,0]
	v_pk_mul_f32 v[42:43], v[42:43], v[82:83] op_sel_hi:[1,0]
	v_pk_mul_f32 v[40:41], v[40:41], v[82:83] op_sel_hi:[1,0]
	v_pk_mul_f32 v[38:39], v[38:39], v[82:83] op_sel_hi:[1,0]
	v_pk_mul_f32 v[36:37], v[36:37], v[82:83] op_sel_hi:[1,0]
	v_pk_mul_f32 v[34:35], v[34:35], v[82:83] op_sel_hi:[1,0]
	v_pk_mul_f32 v[32:33], v[32:33], v[82:83] op_sel_hi:[1,0]
	v_pk_mul_f32 v[14:15], v[14:15], v[82:83] op_sel_hi:[1,0]
	v_pk_mul_f32 v[12:13], v[12:13], v[82:83] op_sel_hi:[1,0]
	v_pk_mul_f32 v[10:11], v[10:11], v[82:83] op_sel_hi:[1,0]
	v_pk_mul_f32 v[8:9], v[8:9], v[82:83] op_sel_hi:[1,0]
	v_pk_mul_f32 v[6:7], v[6:7], v[82:83] op_sel_hi:[1,0]
	v_pk_mul_f32 v[4:5], v[4:5], v[82:83] op_sel_hi:[1,0]
	v_pk_mul_f32 v[2:3], v[2:3], v[82:83] op_sel_hi:[1,0]
	v_pk_mul_f32 v[0:1], v[0:1], v[82:83] op_sel_hi:[1,0]
	v_pk_add_f32 v[82:83], v[90:91], v[126:127]
	s_waitcnt lgkmcnt(2)
	v_mfma_f32_32x32x16_bf16 v[48:63], v[72:75], v[64:67], v[48:63]
	v_add_f32_e64 v82, v106, v82
	v_add_f32_e64 v83, v107, v83
	v_cvt_pk_bf16_f32 v80, v102, v88
	v_lshl_add_u32 v88, v177, 1, v194
	v_add_f32_e64 v82, v122, v82
	v_add_f32_e64 v83, v123, v83
	v_pk_mul_f32 v[18:19], v[18:19], v[160:161] op_sel_hi:[1,0]
	v_pk_add_f32 v[82:83], v[222:223], v[82:83]
	v_pk_mul_f32 v[16:17], v[16:17], v[160:161] op_sel_hi:[1,0]
	v_pk_add_f32 v[82:83], v[92:93], v[82:83]
	v_mfma_f32_32x32x16_bf16 v[32:47], v[72:75], v[68:71], v[32:47]
	v_add_f32_e64 v82, v108, v82
	v_add_f32_e64 v83, v109, v83
	v_cvt_pk_bf16_f32 v81, v120, v90
	v_lshl_add_u32 v102, v176, 1, v194
	v_add_f32_e64 v82, v124, v82
	v_add_f32_e64 v83, v125, v83
	v_lshl_add_u32 v113, v175, 1, v195
	v_pk_add_f32 v[82:83], v[224:225], v[82:83]
	v_lshl_add_u32 v114, v174, 1, v195
	v_pk_add_f32 v[82:83], v[94:95], v[82:83]
	s_waitcnt lgkmcnt(0)
; #define MFMA32(a, b, c) __builtin_amdgcn_mfma_f32_32x32x16_bf16((a), (b), (c), 0, 0, 0)
; DI void attn_pass_da(const bfr* __restrict__ P, int b, int tq_wave, int qcol, int kcol, int vcol, int key0, int nkt, char* smem, f32x16 (&o0)[2], f32x16 (&o1)[2]) {
;     ...
;     bfr* sK = sbase + (kt & 1) * 9216;
;     bfr* sV = sK + 64 * 72;
;     { int c = gt, row = c >> 3, kc = c & 7; *(u32x4*)(sK + row * KP + kc * 8) = kreg[0]; }
;     for (int i = 0; i < 1; ++i) {
;       int c = gt, row = c >> 3, kc = c & 7;
;       unsigned wds[4] = {vreg[i].x, vreg[i].y, vreg[i].z, vreg[i].w};
; #pragma unroll
;       for (int e = 0; e < 4; ++e) {
;         sV[(kc * 8 + 2 * e) * 72 + (row ^ (kc << 3))] = (bfr)(wds[e] & 0xffffu);
;         sV[(kc * 8 + 2 * e + 1) * 72 + (row ^ (kc << 3))] = (bfr)(wds[e] >> 16);
;       }
;     }
;     __syncthreads();
;     if (kt + 1 < nkt) {
;       const bfr* Pn = Pb + (size_t)(kt + 1) * 64 * PW;
;       { int c = gt, row = c >> 3, kc = c & 7; kreg[0] = *(const u32x4*)(Pn + (size_t)row * PW + kcol + kc * 8); vreg[0] = *(const u32x4*)(Pn + (size_t)row * PW + vcol + kc * 8); }
;     }
;     f32x16 s0[2], s1[2];
; #pragma unroll
;     for (int t2 = 0; t2 < 2; ++t2) {
; #pragma unroll
;       for (int i = 0; i < 16; ++i) { s0[t2][i] = 0.f; s1[t2][i] = 0.f; }
; #pragma unroll
;       for (int ks = 0; ks < 2; ++ks) {
;         bf16x8 a0 = *(const bf16x8*)(sK + (t2 * 32 + r) * KP + ks * 16 + h * 8);
;         bf16x8 a1 = *(const bf16x8*)(sK + (t2 * 32 + r) * KP + 32 + ks * 16 + h * 8);
;         s0[t2] = MFMA32(a0, qf[ks], s0[t2]);
;         s1[t2] = MFMA32(a1, qf[2 + ks], s1[t2]);
;       }
;     }
;     ...
;           acc0[dt] = MFMA32(vf, pf0, acc0[dt]);
;           acc1[dt] = MFMA32(vf, pf1, acc1[dt]);
;         }
;       }
	v_mfma_f32_32x32x16_bf16 v[16:31], v[76:79], v[64:67], v[16:31]
	v_add_f32_e64 v84, v110, v82
	v_add_f32_e64 v85, v111, v83
	v_cvt_pk_bf16_f32 v82, v122, v92
	v_cvt_pk_bf16_f32 v83, v124, v94
	v_cvt_pk_bf16_f32 v64, v103, v89
	v_cvt_pk_bf16_f32 v65, v121, v91
	v_cvt_pk_bf16_f32 v66, v123, v93
	v_cvt_pk_bf16_f32 v67, v125, v95
	v_mfma_f32_32x32x16_bf16 v[0:15], v[76:79], v[68:71], v[0:15]
	ds_read_b64 v[68:69], v88 offset:9216
	ds_read_b64 v[70:71], v102 offset:9216
	v_lshl_add_u32 v115, v173, 1, v194
	v_lshl_add_u32 v116, v172, 1, v195
	v_lshl_add_u32 v117, v171, 1, v195
	v_lshl_add_u32 v120, v169, 1, v194
	v_lshl_add_u32 v192, v170, 1, v194
	v_lshl_add_u32 v193, v168, 1, v195
	s_waitcnt lgkmcnt(0)
	v_mfma_f32_32x32x16_bf16 v[48:63], v[68:71], v[80:83], v[48:63]
	v_lshl_add_u32 v194, v167, 1, v195
	v_fma_f32 v156, v156, v160, v84
	v_fma_f32 v157, v157, v161, v85
	v_mfma_f32_32x32x16_bf16 v[32:47], v[68:71], v[64:67], v[32:47]
	ds_read_b64 v[68:69], v113 offset:9216
	ds_read_b64 v[70:71], v114 offset:9216
	s_waitcnt lgkmcnt(0)
	v_mfma_f32_32x32x16_bf16 v[16:31], v[68:71], v[80:83], v[16:31]
	v_mfma_f32_32x32x16_bf16 v[0:15], v[68:71], v[64:67], v[0:15]
	v_cvt_pk_bf16_f32 v64, v212, v96
	v_cvt_pk_bf16_f32 v65, v214, v98
	v_cvt_pk_bf16_f32 v66, v216, v100
	v_cvt_pk_bf16_f32 v67, v218, v86
	v_cvt_pk_bf16_f32 v68, v213, v97
	v_cvt_pk_bf16_f32 v69, v215, v99
	v_cvt_pk_bf16_f32 v70, v217, v101
	v_cvt_pk_bf16_f32 v71, v219, v87
	ds_read_b64 v[72:73], v112 offset:9280
	ds_read_b64 v[74:75], v115 offset:9216
	s_waitcnt lgkmcnt(0)
	v_mfma_f32_32x32x16_bf16 v[48:63], v[72:75], v[64:67], v[48:63]
	v_mfma_f32_32x32x16_bf16 v[32:47], v[72:75], v[68:71], v[32:47]
	ds_read_b64 v[72:73], v116 offset:9216
	ds_read_b64 v[74:75], v117 offset:9216
	s_waitcnt lgkmcnt(0)
	v_mfma_f32_32x32x16_bf16 v[16:31], v[72:75], v[64:67], v[16:31]
	v_cvt_pk_bf16_f32 v64, v118, v104
	v_cvt_pk_bf16_f32 v65, v220, v106
	v_cvt_pk_bf16_f32 v66, v222, v108
	v_cvt_pk_bf16_f32 v67, v224, v110
	v_mfma_f32_32x32x16_bf16 v[0:15], v[72:75], v[68:71], v[0:15]
	v_cvt_pk_bf16_f32 v68, v119, v105
	v_cvt_pk_bf16_f32 v69, v221, v107
	v_cvt_pk_bf16_f32 v70, v223, v109
	v_cvt_pk_bf16_f32 v71, v225, v111
	ds_read_b64 v[72:73], v120 offset:9216
	ds_read_b64 v[74:75], v192 offset:9216
	s_waitcnt lgkmcnt(0)
	v_mfma_f32_32x32x16_bf16 v[48:63], v[72:75], v[64:67], v[48:63]
	v_mfma_f32_32x32x16_bf16 v[32:47], v[72:75], v[68:71], v[32:47]
	ds_read_b64 v[72:73], v193 offset:9216
	ds_read_b64 v[74:75], v194 offset:9216
	s_waitcnt lgkmcnt(0)
	v_mfma_f32_32x32x16_bf16 v[16:31], v[72:75], v[64:67], v[16:31]
	v_mfma_f32_32x32x16_bf16 v[0:15], v[72:75], v[68:71], v[0:15]
	s_cbranch_scc1 .LBB0_421
	v_add3_u32 v64, 0, v206, v152
	s_waitcnt vmcnt(1)
	ds_write_b128 v64, v[148:151] offset:18432
	v_add3_u32 v64, 0, v207, v208
	v_add3_u32 v65, 0, v208, v207
	s_waitcnt vmcnt(0)
	ds_write_b16 v64, v144 offset:27648
	ds_write_b16_d16_hi v65, v144 offset:27792
	ds_write_b16 v64, v145 offset:27936
	ds_write_b16_d16_hi v65, v145 offset:28080
	ds_write_b16 v64, v146 offset:28224
	ds_write_b16_d16_hi v65, v146 offset:28368
	ds_write_b16 v64, v147 offset:28512
	ds_write_b16_d16_hi v65, v147 offset:28656
	v_add_u32_e32 v144, 0, v205
	v_add_u32_e32 v102, v144, v204
	s_waitcnt lgkmcnt(0)
	s_barrier
	ds_read_b128 v[64:67], v102 offset:18432
	ds_read_b128 v[96:99], v102 offset:18464
	s_waitcnt lgkmcnt(1)
	v_mfma_f32_32x32x16_bf16 v[64:79], v[64:67], v[140:143], 0
	ds_read_b128 v[80:83], v102 offset:18496
	v_readlane_b32 s10, v203, 16
	v_readlane_b32 s11, v203, 48
	v_add_u32_e32 v145, 0x1200, v144
	v_mov_b32_e32 v100, s10
	v_mov_b32_e32 v101, s11
	v_pk_add_f32 v[100:101], s[8:9], v[100:101]
	s_mov_b32 s10, 0x3fb8aa3b
	v_add_f32_e32 v146, v100, v101
	v_mul_f32_e32 v104, 0x3fb8aa3b, v146
	v_fma_f32 v105, v146, s10, -v104
	v_rndne_f32_e32 v106, v104
	s_waitcnt lgkmcnt(1)
	v_mfma_f32_32x32x16_bf16 v[64:79], v[96:99], v[132:135], v[64:79]
	v_fmac_f32_e32 v105, 0x32a5705f, v146
	v_sub_f32_e32 v96, v104, v106
	v_add_u32_e32 v147, v145, v204
	v_add_f32_e32 v104, v96, v105
	ds_read_b128 v[96:99], v147 offset:18432
	ds_read_b128 v[100:103], v102 offset:18528
	ds_read_b128 v[112:115], v147 offset:18496
	s_waitcnt lgkmcnt(3)
	v_mfma_f32_32x32x16_bf16 v[80:95], v[80:83], v[136:139], 0
	v_readlane_b32 s8, v202, 16
	v_readlane_b32 s9, v202, 48
	s_mov_b32 s11, 0xc2ce8ed0
	v_mov_b32_e32 v116, s8
	v_mov_b32_e32 v117, s9
	v_pk_add_f32 v[116:117], s[6:7], v[116:117]
	v_cmp_ngt_f32_e32 vcc, s11, v146
	s_waitcnt lgkmcnt(1)
	v_mfma_f32_32x32x16_bf16 v[80:95], v[100:103], v[128:131], v[80:95]
	v_exp_f32_e32 v100, v104
	v_cvt_i32_f32_e32 v101, v106
	v_add_f32_e32 v149, v116, v117
	v_mul_f32_e32 v150, 0x3fb8aa3b, v149
	v_rndne_f32_e32 v151, v150
	v_ldexp_f32 v148, v100, v101
	s_mov_b32 s6, 0x42b17218
	s_waitcnt lgkmcnt(0)
	v_mfma_f32_32x32x16_bf16 v[112:127], v[112:115], v[136:139], 0
	v_fma_f32 v136, v149, s10, -v150
	v_fmac_f32_e32 v136, 0x32a5705f, v149
	v_sub_f32_e32 v137, v150, v151
	v_add_f32_e32 v136, v137, v136
	v_exp_f32_e32 v150, v136
	ds_read_b128 v[136:139], v147 offset:18528
	v_readlane_b32 s8, v253, 28
	v_mfma_f32_32x32x16_bf16 v[96:111], v[96:99], v[140:143], 0
	ds_read_b128 v[140:143], v147 offset:18464
	v_readlane_b32 s9, v253, 29
	s_waitcnt lgkmcnt(0)
; DI void attn_pass_da(const bfr* __restrict__ P, int b, int tq_wave, int qcol, int kcol, int vcol, int key0, int nkt, char* smem, f32x16 (&o0)[2], f32x16 (&o1)[2]) {
;     ...
;     float mx0 = s0[0][0], mx1 = s1[0][0];
; #pragma unroll
;     for (int i = 0; i < 16; ++i) { mx0 = fmaxf(mx0, fmaxf(s0[0][i], s0[1][i])); mx1 = fmaxf(mx1, fmaxf(s1[0][i], s1[1][i])); }
;     mx0 = fmaxf(mx0, __shfl_xor(mx0, 32)); mx1 = fmaxf(mx1, __shfl_xor(mx1, 32));
;     const float mn0 = fmaxf(m0, mx0), mn1 = fmaxf(m1, mx1);
;     const float al0 = __builtin_amdgcn_exp2f(m0 - mn0), al1 = __builtin_amdgcn_exp2f(m1 - mn1);
;     m0 = mn0; m1 = mn1;
;     float ps0 = 0.f, ps1 = 0.f;
; #pragma unroll
;     for (int i = 0; i < 16; ++i) {
;       s0[0][i] = __builtin_amdgcn_exp2f(s0[0][i] - mn0); ps0 += s0[0][i];
;       s0[1][i] = __builtin_amdgcn_exp2f(s0[1][i] - mn0); ps0 += s0[1][i];
;       s1[0][i] = __builtin_amdgcn_exp2f(s1[0][i] - mn1); ps1 += s1[0][i];
;       s1[1][i] = __builtin_amdgcn_exp2f(s1[1][i] - mn1); ps1 += s1[1][i];
;     }
	v_mfma_f32_32x32x16_bf16 v[96:111], v[140:143], v[132:135], v[96:111]
	v_max_f32_e32 v134, v82, v82
	v_max_f32_e32 v135, v67, v67
	v_cvt_i32_f32_e32 v132, v151
	v_cndmask_b32_e32 v133, 0, v148, vcc
	v_cmp_nlt_f32_e32 vcc, s6, v146
	v_ldexp_f32 v132, v150, v132
	v_mfma_f32_32x32x16_bf16 v[112:127], v[136:139], v[128:131], v[112:127]
	s_nop 4
	v_max_f32_e32 v128, v97, v97
	v_max_f32_e32 v129, v65, v65
	v_max_f32_e32 v128, v129, v128
	v_max_f32_e32 v130, v81, v81
	v_max_f32_e32 v131, v66, v66
	v_max3_f32 v128, v64, v96, v128
	v_cndmask_b32_e32 v133, v201, v133, vcc
	v_max_f32_e32 v129, v113, v113
	v_max_f32_e32 v129, v130, v129
	v_max_f32_e32 v130, v98, v98
	v_max_f32_e32 v130, v131, v130
	v_max_f32_e32 v131, v114, v114
	v_max_f32_e32 v131, v134, v131
	v_max_f32_e32 v134, v99, v99
	v_max_f32_e32 v134, v135, v134
	v_max3_f32 v128, v128, v130, v134
	v_max_f32_e32 v130, v115, v115
	v_max_f32_e32 v134, v83, v83
	v_max3_f32 v129, v80, v112, v129
	v_max_f32_e32 v130, v134, v130
	v_max3_f32 v129, v129, v131, v130
	v_max_f32_e32 v130, v100, v100
	v_max_f32_e32 v131, v68, v68
	v_max_f32_e32 v130, v131, v130
	v_max_f32_e32 v131, v116, v116
	v_max_f32_e32 v134, v84, v84
	v_max_f32_e32 v131, v134, v131
	v_max_f32_e32 v134, v101, v101
	v_max_f32_e32 v135, v69, v69
	v_max_f32_e32 v134, v135, v134
	v_max3_f32 v128, v128, v130, v134
	v_max_f32_e32 v130, v117, v117
	v_max_f32_e32 v134, v85, v85
	v_max_f32_e32 v130, v134, v130
	v_max3_f32 v129, v129, v131, v130
	v_max_f32_e32 v130, v102, v102
	v_max_f32_e32 v131, v70, v70
	v_max_f32_e32 v130, v131, v130
	v_max_f32_e32 v131, v118, v118
	v_max_f32_e32 v134, v86, v86
	v_max_f32_e32 v131, v134, v131
	v_max_f32_e32 v134, v103, v103
	v_max_f32_e32 v135, v71, v71
	v_max_f32_e32 v134, v135, v134
	v_max3_f32 v128, v128, v130, v134
	v_max_f32_e32 v130, v119, v119
	v_max_f32_e32 v134, v87, v87
	v_max_f32_e32 v130, v134, v130
	v_max3_f32 v129, v129, v131, v130
	v_max_f32_e32 v130, v104, v104
	v_max_f32_e32 v131, v72, v72
	v_max_f32_e32 v130, v131, v130
	v_max_f32_e32 v131, v120, v120
	v_max_f32_e32 v134, v88, v88
	v_max_f32_e32 v131, v134, v131
	v_max_f32_e32 v134, v105, v105
	v_max_f32_e32 v135, v73, v73
	v_max_f32_e32 v134, v135, v134
	v_max3_f32 v128, v128, v130, v134
	v_max_f32_e32 v130, v121, v121
	v_max_f32_e32 v134, v89, v89
	v_max_f32_e32 v130, v134, v130
	v_max3_f32 v129, v129, v131, v130
	v_max_f32_e32 v130, v106, v106
	v_max_f32_e32 v131, v74, v74
	v_max_f32_e32 v130, v131, v130
	v_max_f32_e32 v131, v122, v122
	v_max_f32_e32 v134, v90, v90
	v_max_f32_e32 v131, v134, v131
	v_max_f32_e32 v134, v107, v107
	v_max_f32_e32 v135, v75, v75
	v_max_f32_e32 v134, v135, v134
	v_max3_f32 v128, v128, v130, v134
	v_max_f32_e32 v130, v123, v123
	v_max_f32_e32 v134, v91, v91
	v_max_f32_e32 v130, v134, v130
	v_max3_f32 v129, v129, v131, v130
	v_max_f32_e32 v130, v108, v108
	v_max_f32_e32 v131, v76, v76
	v_max_f32_e32 v130, v131, v130
	v_max_f32_e32 v131, v124, v124
	v_max_f32_e32 v134, v92, v92
	v_max_f32_e32 v131, v134, v131
	v_max_f32_e32 v134, v109, v109
	v_max_f32_e32 v135, v77, v77
	v_max_f32_e32 v134, v135, v134
	v_max3_f32 v128, v128, v130, v134
	v_max_f32_e32 v130, v125, v125
	v_max_f32_e32 v134, v93, v93
	v_max_f32_e32 v130, v134, v130
	v_max3_f32 v129, v129, v131, v130
	v_max_f32_e32 v130, v110, v110
	v_max_f32_e32 v131, v78, v78
	v_max_f32_e32 v130, v131, v130
	v_max_f32_e32 v131, v126, v126
	v_max_f32_e32 v134, v94, v94
	v_max_f32_e32 v131, v134, v131
	v_max_f32_e32 v134, v111, v111
	v_max_f32_e32 v135, v79, v79
	v_max_f32_e32 v134, v135, v134
	v_max3_f32 v128, v128, v130, v134
	v_max_f32_e32 v130, v127, v127
	v_max_f32_e32 v134, v95, v95
	v_max_f32_e32 v130, v134, v130
	v_max3_f32 v130, v129, v131, v130
	ds_bpermute_b32 v131, v166, v128
	ds_bpermute_b32 v134, v166, v130
	v_cmp_ngt_f32_e32 vcc, s11, v149
	s_waitcnt lgkmcnt(0)
	v_max3_f32 v150, v210, v130, v134
	v_cndmask_b32_e32 v132, 0, v132, vcc
	v_cmp_nlt_f32_e32 vcc, s6, v149
	v_max3_f32 v149, v209, v128, v131
	v_sub_f32_e32 v64, v64, v149
	v_exp_f32_e32 v148, v64
	v_sub_f32_e32 v64, v96, v149
	v_exp_f32_e32 v131, v64
	v_sub_f32_e32 v64, v80, v150
	v_exp_f32_e32 v151, v64
	v_sub_f32_e32 v64, v112, v150
	v_exp_f32_e32 v96, v64
	v_sub_f32_e32 v64, v65, v149
	v_exp_f32_e32 v152, v64
	v_sub_f32_e32 v64, v97, v149
	v_exp_f32_e32 v112, v64
	v_sub_f32_e32 v64, v81, v150
	v_exp_f32_e32 v158, v64
	v_sub_f32_e32 v64, v113, v150
	v_exp_f32_e32 v97, v64
	v_sub_f32_e32 v64, v66, v149
	v_exp_f32_e32 v143, v64
	v_sub_f32_e32 v64, v98, v149
	v_exp_f32_e32 v113, v64
	v_sub_f32_e32 v64, v82, v150
	v_exp_f32_e32 v146, v64
	v_sub_f32_e32 v64, v114, v150
	v_exp_f32_e32 v98, v64
	v_sub_f32_e32 v64, v67, v149
	v_exp_f32_e32 v147, v64
	v_sub_f32_e32 v64, v99, v149
	v_exp_f32_e32 v114, v64
	v_sub_f32_e32 v64, v83, v150
	v_exp_f32_e32 v138, v64
	v_sub_f32_e32 v64, v115, v150
	v_exp_f32_e32 v99, v64
	v_sub_f32_e32 v64, v68, v149
	v_exp_f32_e32 v139, v64
	v_sub_f32_e32 v64, v100, v149
	v_exp_f32_e32 v115, v64
	v_sub_f32_e32 v64, v84, v150
	v_exp_f32_e32 v140, v64
	v_sub_f32_e32 v64, v116, v150
	v_exp_f32_e32 v100, v64
	v_sub_f32_e32 v64, v69, v149
	v_exp_f32_e32 v141, v64
	v_sub_f32_e32 v64, v101, v149
	v_exp_f32_e32 v116, v64
	v_sub_f32_e32 v64, v85, v150
	v_exp_f32_e32 v142, v64
	v_sub_f32_e32 v64, v117, v150
	v_exp_f32_e32 v101, v64
	v_sub_f32_e32 v64, v70, v149
	v_exp_f32_e32 v134, v64
	v_sub_f32_e32 v64, v102, v149
	v_cndmask_b32_e32 v129, v201, v132, vcc
	v_exp_f32_e32 v132, v64
	v_sub_f32_e32 v64, v86, v150
	v_exp_f32_e32 v135, v64
	v_sub_f32_e32 v64, v118, v150
	v_exp_f32_e32 v117, v64
	v_sub_f32_e32 v64, v71, v149
	v_exp_f32_e32 v136, v64
	v_sub_f32_e32 v64, v103, v149
; #define MFMA32(a, b, c) __builtin_amdgcn_mfma_f32_32x32x16_bf16((a), (b), (c), 0, 0, 0)
; DI unsigned pack2(float a, float b) { unsigned r; asm volatile("v_cvt_pk_bf16_f32 %0, %1, %2" : "=v"(r) : "v"(a), "v"(b)); return r; }
; DI void attn_pass_da(const bfr* __restrict__ P, int b, int tq_wave, int qcol, int kcol, int vcol, int key0, int nkt, char* smem, f32x16 (&o0)[2], f32x16 (&o1)[2]) {
;     ...
;     for (int i = 0; i < 16; ++i) {
;       s0[0][i] = __builtin_amdgcn_exp2f(s0[0][i] - mn0); ps0 += s0[0][i];
;       s0[1][i] = __builtin_amdgcn_exp2f(s0[1][i] - mn0); ps0 += s0[1][i];
;       s1[0][i] = __builtin_amdgcn_exp2f(s1[0][i] - mn1); ps1 += s1[0][i];
;       s1[1][i] = __builtin_amdgcn_exp2f(s1[1][i] - mn1); ps1 += s1[1][i];
;     }
;     l0 = l0 * al0 + ps0; l1 = l1 * al1 + ps1;
; #pragma unroll
;     for (int i = 0; i < 16; ++i) { acc0[0][i] *= al0; acc0[1][i] *= al0; acc1[0][i] *= al1; acc1[1][i] *= al1; }
; #pragma unroll
;     for (int t2 = 0; t2 < 2; ++t2)
; #pragma unroll
;       for (int j = 0; j < 2; ++j) {
;         u32x4 pk0, pk1;
;         pk0.x = pack2(s0[t2][8 * j + 0], s0[t2][8 * j + 1]); pk0.y = pack2(s0[t2][8 * j + 2], s0[t2][8 * j + 3]);
;         pk0.z = pack2(s0[t2][8 * j + 4], s0[t2][8 * j + 5]); pk0.w = pack2(s0[t2][8 * j + 6], s0[t2][8 * j + 7]);
;         pk1.x = pack2(s1[t2][8 * j + 0], s1[t2][8 * j + 1]); pk1.y = pack2(s1[t2][8 * j + 2], s1[t2][8 * j + 3]);
;         pk1.z = pack2(s1[t2][8 * j + 4], s1[t2][8 * j + 5]); pk1.w = pack2(s1[t2][8 * j + 6], s1[t2][8 * j + 7]);
;         const bf16x8 pf0 = __builtin_bit_cast(bf16x8, pk0), pf1 = __builtin_bit_cast(bf16x8, pk1);
; #pragma unroll
;         for (int dt = 0; dt < 2; ++dt) {
;           const int vsw = (((dt * 32 + r) >> 3) & 7) << 3;
;           const bfr* vrow = sV + (dt * 32 + r) * 72;
;           s16x4 lo = *(const s16x4*)(vrow + ((t2 * 32 + 16 * j + 4 * h) ^ vsw));
;           s16x4 hi = *(const s16x4*)(vrow + ((t2 * 32 + 16 * j + 4 * h + 8) ^ vsw));
;           bf16x8 vf = __builtin_shufflevector(lo, hi, 0, 1, 2, 3, 4, 5, 6, 7);
;           acc0[dt] = MFMA32(vf, pf0, acc0[dt]);
;           acc1[dt] = MFMA32(vf, pf1, acc1[dt]);
;         }
;       }
	v_sub_f32_e32 v129, v133, v129
	v_exp_f32_e32 v133, v64
	v_sub_f32_e32 v64, v87, v150
	v_exp_f32_e32 v137, v64
	v_sub_f32_e32 v64, v119, v150
	v_exp_f32_e32 v102, v64
	v_sub_f32_e32 v64, v72, v149
	v_exp_f32_e32 v103, v64
	v_sub_f32_e32 v64, v104, v149
	v_exp_f32_e32 v71, v64
	v_sub_f32_e32 v64, v88, v150
	v_exp_f32_e32 v104, v64
	v_sub_f32_e32 v64, v120, v150
	v_exp_f32_e32 v70, v64
	v_sub_f32_e32 v64, v73, v149
	v_exp_f32_e32 v118, v64
	v_sub_f32_e32 v64, v105, v149
	v_exp_f32_e32 v73, v64
	v_sub_f32_e32 v64, v89, v150
	v_exp_f32_e32 v105, v64
	v_sub_f32_e32 v64, v121, v150
	v_exp_f32_e32 v72, v64
	v_sub_f32_e32 v64, v74, v149
	v_exp_f32_e32 v119, v64
	v_sub_f32_e32 v64, v106, v149
	v_exp_f32_e32 v81, v64
	v_sub_f32_e32 v64, v90, v150
	v_exp_f32_e32 v89, v64
	v_sub_f32_e32 v64, v122, v150
	v_exp_f32_e32 v80, v64
	v_sub_f32_e32 v64, v75, v149
	v_exp_f32_e32 v90, v64
	v_sub_f32_e32 v64, v107, v149
	v_exp_f32_e32 v87, v64
	v_sub_f32_e32 v64, v91, v150
	v_exp_f32_e32 v91, v64
	v_sub_f32_e32 v64, v123, v150
	v_exp_f32_e32 v86, v64
	v_sub_f32_e32 v64, v76, v149
	v_exp_f32_e32 v74, v64
	v_sub_f32_e32 v64, v108, v149
	v_exp_f32_e32 v75, v64
	v_sub_f32_e32 v64, v92, v150
	v_exp_f32_e32 v76, v64
	v_sub_f32_e32 v64, v124, v150
	v_exp_f32_e32 v82, v64
	v_sub_f32_e32 v64, v77, v149
	v_exp_f32_e32 v77, v64
	v_sub_f32_e32 v64, v109, v149
	v_exp_f32_e32 v83, v64
	v_sub_f32_e32 v64, v93, v150
	v_exp_f32_e32 v84, v64
	v_sub_f32_e32 v64, v125, v150
	v_exp_f32_e32 v85, v64
	v_sub_f32_e32 v64, v78, v149
	v_exp_f32_e32 v78, v64
	v_sub_f32_e32 v64, v110, v149
	v_exp_f32_e32 v88, v64
	v_sub_f32_e32 v64, v94, v150
	v_exp_f32_e32 v66, v64
	v_sub_f32_e32 v64, v126, v150
	v_exp_f32_e32 v67, v64
	v_sub_f32_e32 v64, v79, v149
	v_exp_f32_e32 v68, v64
	v_sub_f32_e32 v64, v111, v149
	v_lshl_add_u32 v79, v181, 1, v144
	v_lshl_add_u32 v110, v180, 1, v144
	v_lshl_add_u32 v124, v179, 1, v145
	v_lshl_add_u32 v126, v178, 1, v145
	v_exp_f32_e32 v69, v64
	v_sub_f32_e32 v64, v95, v150
	v_sub_f32_e32 v65, v127, v150
	v_cvt_pk_bf16_f32 v92, v148, v152
	v_cvt_pk_bf16_f32 v93, v143, v147
	v_cvt_pk_bf16_f32 v94, v139, v141
	v_cvt_pk_bf16_f32 v95, v134, v136
	v_cvt_pk_bf16_f32 v106, v151, v158
	v_cvt_pk_bf16_f32 v107, v146, v138
	v_cvt_pk_bf16_f32 v108, v140, v142
	v_cvt_pk_bf16_f32 v109, v135, v137
	ds_read_b64 v[120:121], v79 offset:27648
	ds_read_b64 v[122:123], v110 offset:27648
	ds_read_b64 v[124:125], v124 offset:27648
	ds_read_b64 v[126:127], v126 offset:27648
	v_sub_f32_e32 v128, v209, v149
	v_exp_f32_e32 v130, v128
	v_sub_f32_e32 v128, v210, v150
	v_add_f32_e32 v111, 0, v151
	v_exp_f32_e32 v128, v128
	v_add_f32_e32 v110, 0, v148
	v_add_f32_e32 v111, v96, v111
	v_add_f32_e32 v110, v131, v110
	v_add_f32_e32 v111, v158, v111
	v_add_f32_e32 v110, v152, v110
	v_add_f32_e32 v111, v97, v111
	v_add_f32_e32 v110, v112, v110
	v_add_f32_e32 v111, v146, v111
	v_pk_mul_f32 v[46:47], v[46:47], v[128:129] op_sel_hi:[1,0]
	v_pk_mul_f32 v[44:45], v[44:45], v[128:129] op_sel_hi:[1,0]
	v_pk_mul_f32 v[42:43], v[42:43], v[128:129] op_sel_hi:[1,0]
	v_pk_mul_f32 v[40:41], v[40:41], v[128:129] op_sel_hi:[1,0]
	v_pk_mul_f32 v[38:39], v[38:39], v[128:129] op_sel_hi:[1,0]
	v_pk_mul_f32 v[36:37], v[36:37], v[128:129] op_sel_hi:[1,0]
	v_pk_mul_f32 v[34:35], v[34:35], v[128:129] op_sel_hi:[1,0]
	v_pk_mul_f32 v[32:33], v[32:33], v[128:129] op_sel_hi:[1,0]
	v_pk_mul_f32 v[14:15], v[14:15], v[128:129] op_sel_hi:[1,0]
	v_pk_mul_f32 v[12:13], v[12:13], v[128:129] op_sel_hi:[1,0]
	v_pk_mul_f32 v[10:11], v[10:11], v[128:129] op_sel_hi:[1,0]
	v_pk_mul_f32 v[8:9], v[8:9], v[128:129] op_sel_hi:[1,0]
	v_pk_mul_f32 v[6:7], v[6:7], v[128:129] op_sel_hi:[1,0]
	v_pk_mul_f32 v[4:5], v[4:5], v[128:129] op_sel_hi:[1,0]
	v_pk_mul_f32 v[2:3], v[2:3], v[128:129] op_sel_hi:[1,0]
	v_pk_mul_f32 v[0:1], v[0:1], v[128:129] op_sel_hi:[1,0]
	v_add_f32_e32 v110, v143, v110
	v_add_f32_e32 v111, v98, v111
	s_waitcnt lgkmcnt(2)
	v_mfma_f32_32x32x16_bf16 v[32:47], v[120:123], v[106:109], v[32:47]
	v_add_f32_e32 v110, v113, v110
	v_add_f32_e32 v110, v147, v110
	v_add_f32_e32 v110, v114, v110
	v_mul_f32_e64 v62, v62, v130
	v_mul_f32_e64 v63, v63, v130
	v_pk_mul_f32 v[60:61], v[60:61], v[130:131] op_sel_hi:[1,0]
	v_pk_mul_f32 v[58:59], v[58:59], v[130:131] op_sel_hi:[1,0]
	v_pk_mul_f32 v[56:57], v[56:57], v[130:131] op_sel_hi:[1,0]
	s_waitcnt lgkmcnt(0)
	v_mfma_f32_32x32x16_bf16 v[0:15], v[124:127], v[106:109], v[0:15]
	v_add_f32_e32 v106, v138, v111
	v_add_f32_e32 v106, v99, v106
	v_add_f32_e32 v106, v140, v106
	v_add_f32_e32 v107, v139, v110
	v_add_f32_e32 v106, v100, v106
	v_add_f32_e32 v107, v115, v107
	v_add_f32_e32 v106, v142, v106
	v_pk_mul_f32 v[54:55], v[54:55], v[130:131] op_sel_hi:[1,0]
	v_pk_mul_f32 v[52:53], v[52:53], v[130:131] op_sel_hi:[1,0]
	v_pk_mul_f32 v[50:51], v[50:51], v[130:131] op_sel_hi:[1,0]
	v_pk_mul_f32 v[48:49], v[48:49], v[130:131] op_sel_hi:[1,0]
	v_pk_mul_f32 v[30:31], v[30:31], v[130:131] op_sel_hi:[1,0]
	v_pk_mul_f32 v[28:29], v[28:29], v[130:131] op_sel_hi:[1,0]
	v_pk_mul_f32 v[26:27], v[26:27], v[130:131] op_sel_hi:[1,0]
	v_pk_mul_f32 v[24:25], v[24:25], v[130:131] op_sel_hi:[1,0]
	v_pk_mul_f32 v[22:23], v[22:23], v[130:131] op_sel_hi:[1,0]
	v_pk_mul_f32 v[20:21], v[20:21], v[130:131] op_sel_hi:[1,0]
	v_pk_mul_f32 v[18:19], v[18:19], v[130:131] op_sel_hi:[1,0]
	v_pk_mul_f32 v[16:17], v[16:17], v[130:131] op_sel_hi:[1,0]
	v_lshl_add_u32 v143, v177, 1, v144
	v_add_f32_e32 v107, v141, v107
	v_add_f32_e32 v111, v101, v106
	v_lshl_add_u32 v106, v175, 1, v145
	v_lshl_add_u32 v108, v174, 1, v145
	v_exp_f32_e32 v64, v64
	v_mfma_f32_32x32x16_bf16 v[48:63], v[120:123], v[92:95], v[48:63]
	v_add_f32_e32 v110, v116, v107
	v_add_f32_e32 v110, v134, v110
	v_add_f32_e32 v110, v132, v110
	v_add_f32_e32 v110, v136, v110
	v_add_f32_e32 v111, v135, v111
	v_add_f32_e32 v111, v117, v111
	v_exp_f32_e32 v65, v65
	v_mfma_f32_32x32x16_bf16 v[16:31], v[124:127], v[92:95], v[16:31]
	v_cvt_pk_bf16_f32 v92, v103, v118
	v_cvt_pk_bf16_f32 v93, v119, v90
	v_cvt_pk_bf16_f32 v94, v74, v77
	v_cvt_pk_bf16_f32 v95, v78, v68
	v_cvt_pk_bf16_f32 v120, v104, v105
	v_cvt_pk_bf16_f32 v121, v89, v91
	v_cvt_pk_bf16_f32 v122, v76, v84
	v_cvt_pk_bf16_f32 v123, v66, v64
	ds_read_b64 v[146:147], v143 offset:27648
	ds_read_b64 v[106:107], v106 offset:27648
	ds_read_b64 v[108:109], v108 offset:27648
	v_lshl_add_u32 v143, v176, 1, v144
	ds_read_b64 v[148:149], v143 offset:27648
	v_add_f32_e32 v124, v133, v110
	s_waitcnt lgkmcnt(0)
; DI int vhalf() { int h = __builtin_amdgcn_readfirstlane(threadIdx.x >> 8); asm volatile("" : "+s"(h)); return h; }
; #define MFMA32(a, b, c) __builtin_amdgcn_mfma_f32_32x32x16_bf16((a), (b), (c), 0, 0, 0)
; DI void attn_pass_da(const bfr* __restrict__ P, int b, int tq_wave, int qcol, int kcol, int vcol, int key0, int nkt, char* smem, f32x16 (&o0)[2], f32x16 (&o1)[2]) {
;     ...
;           acc0[dt] = MFMA32(vf, pf0, acc0[dt]);
;           acc1[dt] = MFMA32(vf, pf1, acc1[dt]);
;         }
;       }
;   }
;   l0 += __shfl_xor(l0, 32); l1 += __shfl_xor(l1, 32);
;   const float i0 = 1.f / l0, i1 = 1.f / l1;
; #pragma unroll
;   for (int i = 0; i < 16; ++i) { o0[0][i] = acc0[0][i] * i0; o0[1][i] = acc0[1][i] * i0; o1[0][i] = acc1[0][i] * i1; o1[1][i] = acc1[1][i] * i1; }
; DN void da_item(const Params& p, int l, int b, int hd, int tq0, int key0, int nkt, char* smem) {
;     ...
;   float lam = expf(d01) - expf(d23) + lam_init;
;   f32x16 o0[2], o1[2];
;   int tqw = tq0 + vhalf() * 128 + w * 32;
;   attn_pass_da(P, b, tqw, 1152 + hd * 64, 1408 + hd * 64, 1664 + hd * 64, key0, nkt, smem, o0, o1);
;   float ss = 0.f;
; #pragma unroll
;   for (int dt = 0; dt < 2; ++dt)
; #pragma unroll
;     for (int i = 0; i < 16; ++i) { float v = o0[dt][i] - lam * o1[dt][i]; o0[dt][i] = v; ss += v * v; }
	v_mfma_f32_32x32x16_bf16 v[48:63], v[146:149], v[92:95], v[48:63]
	v_add_f32_e32 v125, v137, v111
	v_lshlrev_b32_e32 v152, 1, v154
	v_mfma_f32_32x32x16_bf16 v[16:31], v[106:109], v[92:95], v[16:31]
	v_cvt_pk_bf16_f32 v92, v131, v112
	v_cvt_pk_bf16_f32 v93, v113, v114
	v_cvt_pk_bf16_f32 v94, v115, v116
	v_cvt_pk_bf16_f32 v95, v132, v133
	v_cvt_pk_bf16_f32 v96, v96, v97
	v_cvt_pk_bf16_f32 v97, v98, v99
	v_cvt_pk_bf16_f32 v98, v100, v101
	v_add_f32_e32 v100, v103, v124
	v_add_f32_e32 v100, v71, v100
	v_cvt_pk_bf16_f32 v99, v117, v102
	ds_read_b64 v[110:111], v79 offset:27712
	v_lshl_add_u32 v79, v173, 1, v144
	v_add_f32_e32 v100, v118, v100
	ds_read_b64 v[112:113], v79 offset:27648
	v_add_f32_e32 v79, v102, v125
	v_add_f32_e32 v100, v73, v100
	v_add_f32_e32 v79, v104, v79
	v_add_f32_e32 v104, v119, v100
	v_lshl_add_u32 v100, v172, 1, v145
	v_lshl_add_u32 v102, v171, 1, v145
	ds_read_b64 v[100:101], v100 offset:27648
	ds_read_b64 v[102:103], v102 offset:27648
	v_add_f32_e32 v79, v70, v79
	v_add_f32_e32 v79, v105, v79
	v_add_f32_e32 v79, v72, v79
	v_add_f32_e32 v104, v81, v104
	v_add_f32_e32 v79, v89, v79
	v_add_f32_e32 v79, v80, v79
	v_add_f32_e32 v89, v90, v104
	v_add_f32_e32 v89, v87, v89
	v_add_f32_e32 v79, v91, v79
	v_add_f32_e32 v79, v86, v79
	v_add_f32_e32 v74, v74, v89
	s_waitcnt lgkmcnt(2)
	v_mfma_f32_32x32x16_bf16 v[48:63], v[110:113], v[92:95], v[48:63]
	v_cvt_pk_bf16_f32 v90, v71, v73
	v_cvt_pk_bf16_f32 v91, v81, v87
	v_add_f32_e32 v74, v75, v74
	v_add_f32_e32 v74, v77, v74
	v_add_f32_e32 v74, v83, v74
	v_add_f32_e32 v74, v78, v74
	v_add_f32_e32 v78, v88, v74
	s_waitcnt lgkmcnt(0)
	v_mfma_f32_32x32x16_bf16 v[16:31], v[100:103], v[92:95], v[16:31]
	v_cvt_pk_bf16_f32 v92, v75, v83
	v_add_f32_e32 v75, v76, v79
	v_add_f32_e32 v75, v82, v75
	v_add_f32_e32 v75, v84, v75
	v_add_f32_e32 v79, v85, v75
	v_add_f32_e32 v66, v66, v79
	v_cvt_pk_bf16_f32 v93, v88, v69
	v_mfma_f32_32x32x16_bf16 v[32:47], v[146:149], v[120:123], v[32:47]
	v_cvt_pk_bf16_f32 v70, v70, v72
	v_cvt_pk_bf16_f32 v71, v80, v86
	v_cvt_pk_bf16_f32 v72, v82, v85
	v_cvt_pk_bf16_f32 v73, v67, v65
	v_add_f32_e32 v66, v67, v66
	v_add_f32_e32 v67, v68, v78
	v_add_f32_e32 v67, v69, v67
	v_mfma_f32_32x32x16_bf16 v[0:15], v[106:109], v[120:123], v[0:15]
	v_fmac_f32_e32 v67, v156, v130
	ds_bpermute_b32 v68, v166, v67
	v_lshl_add_u32 v80, v169, 1, v144
	v_lshl_add_u32 v74, v168, 1, v145
	v_lshl_add_u32 v76, v167, 1, v145
	ds_read_b64 v[104:105], v80 offset:27648
	ds_read_b64 v[74:75], v74 offset:27648
	ds_read_b64 v[76:77], v76 offset:27648
	v_lshl_add_u32 v80, v170, 1, v144
	v_add_f32_e32 v64, v64, v66
	ds_read_b64 v[106:107], v80 offset:27648
	v_add_f32_e32 v65, v65, v64
	v_mfma_f32_32x32x16_bf16 v[32:47], v[110:113], v[96:99], v[32:47]
	v_fmac_f32_e32 v65, v157, v128
	s_waitcnt lgkmcnt(4)
	v_add_f32_e32 v66, v67, v68
	ds_bpermute_b32 v67, v166, v65
	v_div_scale_f32 v68, s[6:7], v66, v66, 1.0
	v_rcp_f32_e32 v69, v68
	v_add_f32_e32 v64, v155, v129
	v_mfma_f32_32x32x16_bf16 v[0:15], v[100:103], v[96:99], v[0:15]
	s_waitcnt lgkmcnt(0)
	v_add_f32_e32 v65, v65, v67
	v_fma_f32 v67, -v68, v69, 1.0
	v_fmac_f32_e32 v69, v67, v69
	v_div_scale_f32 v67, vcc, 1.0, v66, 1.0
	v_mfma_f32_32x32x16_bf16 v[32:47], v[104:107], v[70:73], v[32:47]
	v_mfma_f32_32x32x16_bf16 v[0:15], v[74:77], v[70:73], v[0:15]
	v_mul_f32_e32 v70, v67, v69
	v_fma_f32 v71, -v68, v70, v67
	v_fmac_f32_e32 v70, v71, v69
	v_fma_f32 v67, -v68, v70, v67
	v_div_scale_f32 v68, s[6:7], v65, v65, 1.0
	v_rcp_f32_e32 v71, v68
	v_div_fmas_f32 v67, v67, v69, v70
	v_div_fixup_f32 v66, v67, v66, 1.0
	v_mfma_f32_32x32x16_bf16 v[48:63], v[104:107], v[90:93], v[48:63]
	v_fma_f32 v67, -v68, v71, 1.0
	v_fmac_f32_e32 v71, v67, v71
	v_div_scale_f32 v67, vcc, 1.0, v65, 1.0
	v_mul_f32_e32 v69, v67, v71
	v_fma_f32 v70, -v68, v69, v67
	v_fmac_f32_e32 v69, v70, v71
	v_fma_f32 v67, -v68, v69, v67
	v_div_fmas_f32 v67, v67, v71, v69
	v_div_fixup_f32 v68, v67, v65, 1.0
	v_mul_f32_e32 v65, v0, v68
	v_mul_f32_e32 v0, v33, v68
	v_mul_f32_e32 v67, v1, v68
	v_mul_f32_e32 v1, v34, v68
	v_mul_f32_e32 v0, v64, v0
	v_mul_f32_e32 v32, v32, v68
	v_mul_f32_e32 v69, v2, v68
	v_mul_f32_e32 v2, v35, v68
	v_mul_f32_e32 v33, v37, v68
	v_mul_f32_e32 v37, v41, v68
	v_mul_f32_e32 v41, v45, v68
	v_fma_f32 v45, v49, v66, -v0
	v_mul_f32_e32 v0, v64, v1
	v_mul_f32_e32 v70, v3, v68
	v_mul_f32_e32 v3, v36, v68
	v_mul_f32_e32 v35, v39, v68
	v_mul_f32_e32 v39, v43, v68
	v_mul_f32_e32 v43, v47, v68
	v_mul_f32_e32 v32, v64, v32
	v_fma_f32 v47, v50, v66, -v0
	v_mul_f32_e32 v0, v64, v2
	v_mul_f32_e32 v36, v40, v68
	v_mul_f32_e32 v40, v44, v68
	v_fma_f32 v44, v48, v66, -v32
	v_fma_f32 v48, v51, v66, -v0
	v_mul_f32_e32 v0, v64, v3
	v_mul_f32_e32 v34, v38, v68
	v_fma_f32 v49, v52, v66, -v0
	v_mul_f32_e32 v0, v64, v33
	s_mov_b32 s6, 23
	v_fma_f32 v50, v53, v66, -v0
	v_mul_f32_e32 v0, v64, v34
	s_ashr_i32 s7, s6, 31
	v_fma_f32 v51, v54, v66, -v0
	v_mul_f32_e32 v0, v64, v35
	s_lshl_b64 s[6:7], s[6:7], 3
	v_fma_f32 v52, v55, v66, -v0
	v_mul_f32_e32 v0, v64, v36
	s_add_u32 s6, s0, s6
	v_mul_f32_e32 v38, v42, v68
	v_fma_f32 v53, v56, v66, -v0
	v_mul_f32_e32 v0, v64, v37
	s_addc_u32 s7, s1, s7
	v_fma_f32 v54, v57, v66, -v0
	v_mul_f32_e32 v0, v64, v38
	s_load_dwordx2 s[6:7], s[6:7], 0x0
	v_mul_f32_e32 v42, v46, v68
	v_mul_f32_e32 v46, v45, v45
	v_fma_f32 v55, v58, v66, -v0
	v_mul_f32_e32 v0, v64, v39
	v_fmac_f32_e32 v46, v44, v44
	v_fma_f32 v56, v59, v66, -v0
	v_mul_f32_e32 v0, v64, v40
	v_fmac_f32_e32 v46, v47, v47
	v_fma_f32 v57, v60, v66, -v0
	v_mul_f32_e32 v0, v64, v41
	v_fmac_f32_e32 v46, v48, v48
	v_fma_f32 v58, v61, v66, -v0
	s_lshl_b64 s[8:9], s[8:9], 2
	v_lshrrev_b32_e32 v0, 3, v164
	v_fmac_f32_e32 v46, v49, v49
	s_waitcnt lgkmcnt(0)
; DI int oidx(int i) { asm volatile("" : "+s"(i)); return i; }
; DI unsigned pack2(float a, float b) { unsigned r; asm volatile("v_cvt_pk_bf16_f32 %0, %1, %2" : "=v"(r) : "v"(a), "v"(b)); return r; }
; DI void store_o(bfr* O, int m, int colbase, int h, const f32x16 (&o)[2]) {
; #pragma unroll
;   for (int dt = 0; dt < 2; ++dt)
; #pragma unroll
;     for (int g4 = 0; g4 < 4; ++g4) {
;       int dv = dt * 32 + 8 * g4 + 4 * h;
;       uint2 pk; pk.x = pack2(o[dt][4 * g4], o[dt][4 * g4 + 1]); pk.y = pack2(o[dt][4 * g4 + 2], o[dt][4 * g4 + 3]);
;       *(uint2*)(O + (size_t)m * DM + colbase + dv) = pk;
;     }
; }
; DN void da_item(const Params& p, int l, int b, int hd, int tq0, int key0, int nkt, char* smem) {
;     ...
;     for (int i = 0; i < 16; ++i) { float v = o0[dt][i] - lam * o1[dt][i]; o0[dt][i] = v; ss += v * v; }
;   ss += __shfl_xor(ss, 32);
;   float rstd = rsqrtf(ss * (1.f / 64.f) + 1e-6f) * (1.f - lam_init);
;   const float* sg = p.in[oidx(23)] + l * 64;
; #pragma unroll
;   for (int dt = 0; dt < 2; ++dt)
; #pragma unroll
;     for (int i = 0; i < 16; ++i) { int dv = dt * 32 + 8 * (i >> 2) + 4 * h + (i & 3); o0[dt][i] = o0[dt][i] * rstd * sg[dv]; }
;   store_o(O, b * TT + tqw + r, 256 + hd * 64, h, o0);
	s_add_u32 s6, s6, s8
	v_and_b32_e32 v59, 4, v0
	v_fmac_f32_e32 v46, v50, v50
	s_addc_u32 s7, s7, s9
	v_lshlrev_b32_e32 v60, 2, v59
	v_mfma_f32_32x32x16_bf16 v[16:31], v[74:77], v[90:93], v[16:31]
	v_fmac_f32_e32 v46, v51, v51
	global_load_dwordx4 v[0:3], v60, s[6:7]
	v_fmac_f32_e32 v46, v52, v52
	v_fmac_f32_e32 v46, v53, v53
	v_mul_f32_e32 v32, v64, v42
	v_fmac_f32_e32 v46, v54, v54
	v_fma_f32 v61, v62, v66, -v32
	v_mul_f32_e32 v32, v64, v43
	v_fmac_f32_e32 v46, v55, v55
	v_fma_f32 v62, v63, v66, -v32
	global_load_dwordx4 v[32:35], v60, s[6:7] offset:32
	v_fmac_f32_e32 v46, v56, v56
	v_fmac_f32_e32 v46, v57, v57
	v_fmac_f32_e32 v46, v58, v58
	v_mul_f32_e32 v36, v64, v65
	v_fmac_f32_e32 v46, v61, v61
	v_fma_f32 v63, v16, v66, -v36
	v_mul_f32_e32 v16, v64, v67
	global_load_dwordx4 v[36:39], v60, s[6:7] offset:64
	v_mul_f32_e32 v4, v4, v68
	v_fmac_f32_e32 v46, v62, v62
	v_fma_f32 v65, v17, v66, -v16
	v_mul_f32_e32 v16, v64, v69
	v_mul_f32_e32 v5, v5, v68
	v_fmac_f32_e32 v46, v63, v63
	v_fma_f32 v67, v18, v66, -v16
	v_mul_f32_e32 v16, v64, v70
	v_mul_f32_e32 v4, v64, v4
	v_fmac_f32_e32 v46, v65, v65
	v_fma_f32 v69, v19, v66, -v16
	v_fma_f32 v70, v20, v66, -v4
	v_mul_f32_e32 v4, v64, v5
	v_fmac_f32_e32 v46, v67, v67
	global_load_dwordx4 v[16:19], v60, s[6:7] offset:96
	v_fma_f32 v71, v21, v66, -v4
	v_pk_mul_f32 v[4:5], v[6:7], v[68:69] op_sel_hi:[1,0]
	v_fmac_f32_e32 v46, v69, v69
	v_pk_mul_f32 v[4:5], v[64:65], v[4:5] op_sel_hi:[0,1]
	v_fmac_f32_e32 v46, v70, v70
	v_pk_fma_f32 v[40:41], v[22:23], v[66:67], v[4:5] op_sel_hi:[1,0,1] neg_lo:[0,0,1] neg_hi:[0,0,1]
	v_pk_mul_f32 v[8:9], v[8:9], v[68:69] op_sel_hi:[1,0]
	v_fmac_f32_e32 v46, v71, v71
	v_pk_mul_f32 v[20:21], v[40:41], v[40:41]
	v_pk_mul_f32 v[8:9], v[64:65], v[8:9] op_sel_hi:[0,1]
	global_load_dwordx4 v[4:7], v60, s[6:7] offset:128
	v_add_f32_e32 v20, v20, v46
	v_pk_fma_f32 v[24:25], v[24:25], v[66:67], v[8:9] op_sel_hi:[1,0,1] neg_lo:[0,0,1] neg_hi:[0,0,1]
	v_add_f32_e32 v20, v21, v20
	v_pk_mul_f32 v[8:9], v[24:25], v[24:25]
	v_pk_mul_f32 v[12:13], v[12:13], v[68:69] op_sel_hi:[1,0]
	v_add_f32_e32 v8, v8, v20
	v_add_f32_e32 v42, v9, v8
	v_pk_mul_f32 v[8:9], v[10:11], v[68:69] op_sel_hi:[1,0]
	global_load_dwordx4 v[20:23], v60, s[6:7] offset:160
	v_pk_mul_f32 v[8:9], v[64:65], v[8:9] op_sel_hi:[0,1]
	v_pk_fma_f32 v[26:27], v[26:27], v[66:67], v[8:9] op_sel_hi:[1,0,1] neg_lo:[0,0,1] neg_hi:[0,0,1]
	v_pk_mul_f32 v[12:13], v[64:65], v[12:13] op_sel_hi:[0,1]
	v_pk_mul_f32 v[8:9], v[26:27], v[26:27]
	v_pk_fma_f32 v[28:29], v[28:29], v[66:67], v[12:13] op_sel_hi:[1,0,1] neg_lo:[0,0,1] neg_hi:[0,0,1]
	v_add_f32_e32 v8, v8, v42
	v_add_f32_e32 v42, v9, v8
	global_load_dwordx4 v[8:11], v60, s[6:7] offset:192
	v_pk_mul_f32 v[12:13], v[28:29], v[28:29]
	s_load_dwordx4 s[8:11], s[0:1], 0x100
	v_add_f32_e32 v12, v12, v42
	v_add_f32_e32 v46, v13, v12
	v_pk_mul_f32 v[42:43], v[14:15], v[68:69] op_sel_hi:[1,0]
	global_load_dwordx4 v[12:15], v60, s[6:7] offset:224
	v_pk_mul_f32 v[42:43], v[64:65], v[42:43] op_sel_hi:[0,1]
	v_pk_fma_f32 v[30:31], v[30:31], v[66:67], v[42:43] op_sel_hi:[1,0,1] neg_lo:[0,0,1] neg_hi:[0,0,1]
	s_mov_b64 s[6:7], 0x2b7c300
	v_pk_mul_f32 v[42:43], v[30:31], v[30:31]
	s_nop 0
	v_add_f32_e32 v42, v42, v46
	v_add_f32_e32 v42, v43, v42
	ds_bpermute_b32 v43, v166, v42
	s_waitcnt lgkmcnt(0)
	v_add_f32_e32 v42, v42, v43
	v_fmamk_f32 v42, v42, 0x3c800000, v186
	v_cmp_gt_f32_e32 vcc, s33, v42
	v_mul_f32_e32 v43, 0x4b800000, v42
	s_nop 0
	v_cndmask_b32_e32 v42, v42, v43, vcc
	v_rsq_f32_e32 v42, v42
	s_nop 0
	v_mul_f32_e32 v43, 0x45800000, v42
	v_cndmask_b32_e32 v42, v42, v43, vcc
	v_mul_f32_e32 v42, v162, v42
	v_mul_f32_e32 v43, v44, v42
	s_waitcnt vmcnt(7)
	v_mul_f32_e32 v43, v0, v43
	v_mul_f32_e32 v0, v45, v42
	v_mul_f32_e32 v44, v1, v0
	v_mul_f32_e32 v0, v47, v42
	v_mul_f32_e32 v45, v2, v0
	v_mul_f32_e32 v0, v48, v42
	v_mul_f32_e32 v3, v3, v0
	v_mul_f32_e32 v0, v49, v42
	s_waitcnt vmcnt(6)
	v_mul_f32_e32 v32, v32, v0
	v_mul_f32_e32 v0, v50, v42
	v_mul_f32_e32 v33, v33, v0
	v_mul_f32_e32 v0, v51, v42
	v_mul_f32_e32 v34, v34, v0
	v_mul_f32_e32 v0, v52, v42
	v_mul_f32_e32 v35, v35, v0
	v_mul_f32_e32 v0, v53, v42
	s_waitcnt vmcnt(5)
	v_mul_f32_e32 v36, v36, v0
	v_mul_f32_e32 v0, v54, v42
	v_mul_f32_e32 v37, v37, v0
	v_mul_f32_e32 v0, v55, v42
	v_mul_f32_e32 v38, v38, v0
	v_mul_f32_e32 v0, v56, v42
	v_mul_f32_e32 v39, v39, v0
	v_mul_f32_e32 v0, v57, v42
	s_waitcnt vmcnt(4)
	v_mul_f32_e32 v16, v16, v0
	v_mul_f32_e32 v0, v58, v42
	v_mul_f32_e32 v17, v17, v0
	v_mul_f32_e32 v0, v61, v42
	v_mul_f32_e32 v18, v18, v0
	v_mul_f32_e32 v0, v62, v42
	v_mul_f32_e32 v19, v19, v0
	v_mul_f32_e32 v0, v63, v42
	s_waitcnt vmcnt(3)
	v_mul_f32_e32 v46, v4, v0
	v_mul_f32_e32 v0, v65, v42
	v_mul_f32_e32 v47, v5, v0
	v_mul_f32_e32 v0, v67, v42
	v_mul_f32_e32 v6, v6, v0
	v_mul_f32_e32 v0, v69, v42
	v_mul_f32_e32 v7, v7, v0
	v_mul_f32_e32 v0, v70, v42
	s_waitcnt vmcnt(2)
	v_mul_f32_e32 v20, v20, v0
	v_mul_f32_e32 v0, v71, v42
	v_mul_f32_e32 v21, v21, v0
	v_mul_f32_e32 v0, v40, v42
	v_mul_f32_e32 v22, v22, v0
	v_mul_f32_e32 v0, v41, v42
	v_mul_f32_e32 v23, v23, v0
	v_mul_f32_e32 v0, v24, v42
	s_waitcnt vmcnt(1)
	v_mul_f32_e32 v8, v8, v0
	v_mul_f32_e32 v0, v25, v42
	v_mul_f32_e32 v9, v9, v0
	v_mul_f32_e32 v0, v26, v42
	v_mul_f32_e32 v10, v10, v0
	v_mul_f32_e32 v0, v27, v42
	v_mul_f32_e32 v11, v11, v0
	v_mul_f32_e32 v0, v28, v42
	s_waitcnt vmcnt(0)
	v_mul_f32_e32 v12, v12, v0
	v_mul_f32_e32 v0, v29, v42
	v_mul_f32_e32 v13, v13, v0
	v_mul_f32_e32 v0, v30, v42
	v_mul_f32_e32 v14, v14, v0
	v_mul_f32_e32 v0, v31, v42
	v_mul_f32_e32 v15, v15, v0
	v_and_or_b32 v0, v164, 31, v165
	v_ashrrev_i32_e32 v1, 31, v0
	v_lshlrev_b64 v[0:1], 11, v[0:1]
	v_lshl_add_u64 v[0:1], s[10:11], 0, v[0:1]
	v_lshl_add_u64 v[0:1], v[0:1], 0, v[152:153]
	v_lshlrev_b32_e32 v152, 1, v59
	v_lshl_add_u64 v[0:1], v[0:1], 0, v[152:153]
	v_lshl_add_u64 v[4:5], v[0:1], 0, s[6:7]
	s_mov_b32 s6, 0x2b7c000
	v_add_co_u32_e32 v0, vcc, s6, v0
	v_cvt_pk_bf16_f32 v2, v43, v44
	v_cvt_pk_bf16_f32 v3, v45, v3
	s_nop 1
	v_addc_co_u32_e32 v1, vcc, 0, v1, vcc
	global_store_dwordx2 v[0:1], v[2:3], off offset:768
	v_cvt_pk_bf16_f32 v0, v32, v33
	v_cvt_pk_bf16_f32 v1, v34, v35
	global_store_dwordx2 v[4:5], v[0:1], off offset:16
	v_cvt_pk_bf16_f32 v0, v36, v37
	v_cvt_pk_bf16_f32 v1, v38, v39
	global_store_dwordx2 v[4:5], v[0:1], off offset:32
	v_cvt_pk_bf16_f32 v0, v16, v17
	v_cvt_pk_bf16_f32 v1, v18, v19
	global_store_dwordx2 v[4:5], v[0:1], off offset:48
	v_cvt_pk_bf16_f32 v0, v46, v47
	v_cvt_pk_bf16_f32 v1, v6, v7
	global_store_dwordx2 v[4:5], v[0:1], off offset:64
	v_cvt_pk_bf16_f32 v0, v20, v21
	v_cvt_pk_bf16_f32 v1, v22, v23
	global_store_dwordx2 v[4:5], v[0:1], off offset:80
	v_cvt_pk_bf16_f32 v0, v8, v9
	v_cvt_pk_bf16_f32 v1, v10, v11
	global_store_dwordx2 v[4:5], v[0:1], off offset:96
	v_cvt_pk_bf16_f32 v0, v12, v13
	v_cvt_pk_bf16_f32 v1, v14, v15
	global_store_dwordx2 v[4:5], v[0:1], off offset:112
